# scan body hand-scheduled (column-packed pairs, no nops), helper-wave loads batched, final-norm pass software pipelined
# speedup vs baseline: 1.0380x; 1.0380x over previous
.LBB0_1840:
	s_or_b64 exec, exec, s[50:51]
	s_lshl_b32 s50, s89, 1
	s_lshl_b32 s61, s90, 1
	s_and_b32 s60, s50, 0x380
	s_add_i32 s52, s65, s61
	s_cmpk_lt_i32 s52, 0x1fc
	s_mul_hi_i32 s50, s52, 0x81020409
	s_cselect_b64 s[58:59], -1, 0
	s_add_i32 s50, s50, s52
	s_lshr_b32 s51, s50, 31
	s_ashr_i32 s50, s50, 7
	s_add_i32 s56, s50, s51
	s_mul_i32 s50, s56, 0xffffff02
	s_add_i32 s50, s50, s52
	v_lshl_or_b32 v4, s50, 4, v150
	s_mov_b32 s50, 0x81020409
	v_mul_hi_i32 v5, v4, s50
	v_add_u32_e32 v5, v5, v4
	v_lshrrev_b32_e32 v6, 31, v5
	v_ashrrev_i32_e32 v5, 7, v5
	v_add_u32_e32 v169, v5, v6
	s_movk_i32 s50, 0xff02
	v_mad_u64_u32 v[4:5], s[50:51], v169, s50, v[4:5]
	s_add_i32 s50, s52, 0xfd
	s_cmpk_lt_u32 s50, 0x1fb
	s_cselect_b64 s[52:53], -1, 0
	s_cmpk_gt_u32 s50, 0x1fa
	v_ashrrev_i32_e32 v126, 1, v4
	s_cselect_b64 s[50:51], -1, 0
	s_and_b64 s[54:55], s[52:53], exec
	v_lshlrev_b32_e32 v4, 11, v169
	v_readlane_b32 s68, v251, 24
	v_lshl_add_u32 v6, v126, 4, v4
	v_mov_b64_e32 v[4:5], s[28:29]
	s_movk_i32 s54, 0x600
	v_readlane_b32 s73, v251, 29
	v_readlane_b32 s74, v251, 30
	v_readlane_b32 s82, v251, 38
	v_readlane_b32 s83, v251, 39
	v_mad_i64_i32 v[4:5], s[54:55], v6, s54, v[4:5]
	s_cselect_b32 s73, s83, s37
	s_cselect_b32 s74, s82, s36
	s_lshl_b32 s54, s56, 7
	s_ashr_i32 s55, s54, 31
	v_lshl_add_u64 v[4:5], s[54:55], 1, v[4:5]
	s_add_u32 s54, s33, s22
	s_addc_u32 s55, s64, s23
	s_and_b64 s[22:23], s[52:53], exec
	s_mov_b32 s22, 0x2a00000
	s_cselect_b32 s56, s22, 0x2a80000
	s_add_u32 s54, s54, s26
	s_addc_u32 s55, s55, 0
	s_add_i32 s22, s66, s61
	v_mov_b32_e32 v121, v9
	s_lshl_b32 s23, s22, 3
	s_lshr_b32 s22, s22, 2
	v_lshl_add_u64 v[4:5], v[4:5], 0, v[120:121]
	v_mov_b32_e32 v123, v9
	s_and_b32 s22, s22, 64
	s_lshl_b64 s[0:1], s[0:1], 21
	v_mov_b32_e32 v12, v9
	v_mov_b32_e32 v13, v9
	v_readlane_b32 s75, v251, 31
	v_readlane_b32 s76, v251, 32
	s_mov_b32 s57, 0
	v_lshl_add_u64 v[130:131], v[4:5], 0, v[122:123]
	v_mov_b32_e32 v119, v9
	v_or_b32_e32 v4, s22, v152
	s_or_b32 s0, s0, s60
	v_mov_b32_e32 v8, v9
	v_mov_b32_e32 v10, v9
	v_mov_b32_e32 v11, v9
	v_mov_b64_e32 v[16:17], v[12:13]
	v_mov_b64_e32 v[20:21], v[12:13]
	v_mov_b64_e32 v[24:25], v[12:13]
	v_mov_b64_e32 v[28:29], v[12:13]
	v_mov_b64_e32 v[32:33], v[12:13]
	v_mov_b64_e32 v[40:41], v[12:13]
	v_mov_b64_e32 v[52:53], v[12:13]
	v_lshl_add_u64 v[128:129], v[104:105], 0, s[56:57]
	s_and_b64 s[58:59], s[30:31], s[58:59]
	v_lshl_add_u64 v[132:133], s[54:55], 0, v[118:119]
	s_and_b32 s56, s23, 0x7f8
	v_lshl_add_u64 v[134:135], v[116:117], 0, s[0:1]
	v_lshl_add_u64 v[136:137], v[0:1], 0, s[48:49]
	v_lshl_add_u64 v[138:139], v[2:3], 0, s[48:49]
	s_mov_b32 s75, 0xffc00000
	s_mov_b64 s[60:61], 0
	s_lshl_b32 s26, s22, 1
	v_lshlrev_b32_e32 v119, 12, v4
	s_mov_b64 s[62:63], 0
	v_mov_b64_e32 v[14:15], v[10:11]
	v_mov_b64_e32 v[18:19], v[10:11]
	v_mov_b64_e32 v[22:23], v[10:11]
	v_mov_b64_e32 v[26:27], v[10:11]
	v_mov_b64_e32 v[30:31], v[10:11]
	v_mov_b64_e32 v[38:39], v[10:11]
	v_mov_b64_e32 v[50:51], v[10:11]
	v_mov_b64_e32 v[54:55], v[8:9]
	v_mov_b64_e32 v[56:57], v[8:9]
	v_mov_b64_e32 v[66:67], v[8:9]
	v_mov_b64_e32 v[68:69], v[8:9]
	s_mov_b32 s76, s57
	v_readlane_b32 s69, v251, 25
	v_readlane_b32 s70, v251, 26
	v_readlane_b32 s71, v251, 27
	v_readlane_b32 s72, v251, 28
	v_readlane_b32 s77, v251, 33
	v_readlane_b32 s78, v251, 34
	v_readlane_b32 s79, v251, 35
	v_readlane_b32 s80, v251, 36
	v_readlane_b32 s81, v251, 37
	s_branch .LBB0_1843
.LBB0_1842:
	s_add_u32 s62, s62, 0x8000
	s_addc_u32 s63, s63, 0
	s_add_i32 s57, s57, 32
	s_add_i32 s75, s75, 0x10000
	s_add_u32 s60, s60, 64
	s_addc_u32 s61, s61, 0
	s_add_i32 s76, s76, 1
	s_cmpk_eq_i32 s60, 0x1000
	s_cbranch_scc1 .LBB0_1929

.LBB0_1859:
	s_or_b64 exec, exec, s[0:1]
	s_andn2_b64 vcc, exec, s[34:35]
	s_cbranch_vccnz .LBB0_1862
	s_add_i32 s22, s67, s75
	s_add_i32 s0, s22, 0x3ffe80
	s_ashr_i32 s23, s0, 7
	v_mad_i64_i32 v[0:1], s[0:1], s23, v164, v[106:107]
	s_add_i32 s22, s22, 0x407e80
	s_ashr_i32 s22, s22, 7
	s_lshl_b32 s0, s23, 5
	s_and_b32 s0, s0, 0xffe0
	v_or_b32_e32 v2, s0, v154
	v_mad_i64_i32 v[4:5], s[0:1], s22, v164, v[106:107]
	v_lshlrev_b32_e32 v2, 3, v2
	s_lshl_b32 s0, s22, 5
	s_and_b32 s0, s0, 0xffe0
	v_or_b32_e32 v3, s0, v154
	v_lshlrev_b32_e32 v3, 3, v3
	global_load_ushort v58, v[0:1], off
	global_load_ushort v59, v[0:1], off offset:64
	global_load_dwordx2 v[60:61], v2, s[40:41]
	global_load_ushort v62, v[4:5], off
	global_load_ushort v63, v[4:5], off offset:64
	global_load_dwordx2 v[64:65], v3, s[40:41]
	s_cmp_gt_u32 s76, 31
	s_cbranch_scc1 .Lrope_wait
	v_add_u32_e32 v80, s62, v114
	v_bfe_u32 v84, v80, 15, 4
	v_lshl_or_b32 v78, v84, 11, s56
	v_mul_u32_u24_e32 v78, 0x300, v78
	s_mov_b32 s0, 0x80000
	v_lshlrev_b32_e32 v86, 1, v78
	v_mov_b32_e32 v87, 0
	v_cmp_gt_u32_e32 vcc, s0, v80
	v_lshl_add_u64 v[78:79], s[28:29], 0, v[86:87]
	v_mov_b32_e32 v125, v9
	v_cndmask_b32_e32 v86, v165, v166, vcc
	v_lshl_add_u64 v[78:79], v[78:79], 0, v[86:87]
	v_lshl_add_u64 v[78:79], v[78:79], 0, s[26:27]
	v_lshl_add_u64 v[82:83], v[78:79], 0, v[124:125]
	s_movk_i32 s0, 0x1000
	s_mov_b32 s1, 0
	v_lshl_add_u64 v[80:81], v[82:83], 0, s[0:1]
	global_load_ushort v70, v[82:83], off
	global_load_ushort v71, v[82:83], off offset:1536
	global_load_ushort v72, v[82:83], off offset:3072
	global_load_ushort v73, v[80:81], off offset:512
	global_load_ushort v74, v[80:81], off offset:2048
	global_load_ushort v75, v[80:81], off offset:3584
	v_lshl_add_u64 v[80:81], v[80:81], 0, s[0:1]
	global_load_ushort v76, v[80:81], off offset:1024
	global_load_ushort v77, v[80:81], off offset:2560
.Lrope_wait:
	s_waitcnt vmcnt(0)
	v_lshlrev_b32_e32 v58, 16, v58
	v_lshlrev_b32_e32 v59, 16, v59
	v_lshlrev_b32_e32 v62, 16, v62
	v_lshlrev_b32_e32 v63, 16, v63
	v_mul_f32_e32 v6, v61, v59
	v_mul_f32_e32 v7, v60, v59
	v_mul_f32_e32 v88, v65, v63
	v_mul_f32_e32 v89, v64, v63
	v_fma_f32 v6, v60, v58, -v6
	v_fmac_f32_e32 v7, v61, v58
	v_fma_f32 v88, v64, v62, -v88
	v_fmac_f32_e32 v89, v65, v62
	v_bfe_u32 v2, v6, 16, 1
	v_bfe_u32 v3, v7, 16, 1
	v_bfe_u32 v140, v88, 16, 1
	v_bfe_u32 v141, v89, 16, 1
	v_add3_u32 v6, v6, v2, s85
	v_add3_u32 v7, v7, v3, s85
	v_add3_u32 v88, v88, v140, s85
	v_add3_u32 v89, v89, v141, s85
	global_store_short_d16_hi v[0:1], v6, off
	global_store_short_d16_hi v[0:1], v7, off offset:64
	global_store_short_d16_hi v[4:5], v88, off
	global_store_short_d16_hi v[4:5], v89, off offset:64
	s_cmp_gt_u32 s76, 31
	s_cbranch_scc1 .LBB0_1862
	v_lshl_or_b32 v70, v71, 16, v70
	v_lshl_or_b32 v71, v73, 16, v72
	v_lshl_or_b32 v72, v75, 16, v74
	v_lshl_or_b32 v73, v77, 16, v76
	v_cndmask_b32_e32 v86, v167, v168, vcc
	v_lshl_add_u64 v[82:83], s[96:97], 0, v[86:87]
	v_lshl_or_b32 v86, v84, 19, v119
	v_lshl_add_u64 v[82:83], v[82:83], 0, v[86:87]
	s_lshl_b32 s0, s56, 1
	s_mov_b32 s1, s27
	v_lshl_add_u64 v[82:83], v[82:83], 0, s[0:1]
	global_store_dwordx4 v[82:83], v[70:73], off
.LBB0_1862:
	s_nop 1
	v_cndmask_b32_e64 v0, 0, 1, s[58:59]
	v_cmp_ne_u32_e64 s[22:23], 1, v0
	s_andn2_b64 vcc, exec, s[58:59]
	s_cbranch_vccnz .LBB0_1864
	s_lshr_b32 s78, s76, 1
	s_and_b32 s79, s57, 32
	s_mul_i32 s0, s78, 0x300
	s_mov_b32 s1, s27
	v_lshl_add_u64 v[0:1], s[0:1], 1, v[130:131]
	s_lshl_b32 s0, s79, 1
	v_lshl_add_u64 v[0:1], v[0:1], 0, s[0:1]
	s_lshl_b32 s0, s78, 6
	s_lshl_b64 s[0:1], s[0:1], 2
	s_add_u32 s0, s74, s0
	s_addc_u32 s1, s73, s1
	s_lshl_b32 s78, s79, 2
	s_add_u32 s0, s0, s78
	global_load_dwordx4 v[0:3], v[0:1], off
	s_addc_u32 s1, s1, 0
	v_lshlrev_b32_e32 v8, 2, v100
	global_load_dwordx4 v[4:7], v8, s[0:1] offset:16
	global_load_dwordx4 v[58:61], v8, s[0:1]
	v_lshl_add_u64 v[62:63], v[128:129], 0, s[60:61]
	s_mov_b32 s78, 0x10000
	s_mov_b32 s79, 0
	global_load_dwordx4 v[70:73], v[62:63], off
	v_lshl_add_u64 v[62:63], v[62:63], 0, s[78:79]
	global_load_dwordx4 v[74:77], v[62:63], off
	v_lshl_add_u64 v[62:63], v[62:63], 0, s[78:79]
	global_load_dwordx4 v[78:81], v[62:63], off
	v_lshl_add_u64 v[62:63], v[62:63], 0, s[78:79]
	global_load_dwordx4 v[82:85], v[62:63], off
	v_lshl_add_u64 v[62:63], v[62:63], 0, s[78:79]
	global_load_dwordx4 v[86:89], v[62:63], off
	v_lshl_add_u64 v[62:63], v[62:63], 0, s[78:79]
	global_load_dwordx4 v[140:143], v[62:63], off
	v_lshl_add_u64 v[62:63], v[62:63], 0, s[78:79]
	global_load_dwordx4 v[144:147], v[62:63], off
	v_lshl_add_u64 v[62:63], v[62:63], 0, s[78:79]
	global_load_dwordx4 v[170:173], v[62:63], off
	s_waitcnt vmcnt(10)
	v_lshlrev_b32_e32 v62, 16, v0
	v_and_b32_e32 v63, 0xffff0000, v0
	v_lshlrev_b32_e32 v0, 16, v1
	v_and_b32_e32 v1, 0xffff0000, v1
	s_waitcnt vmcnt(8)
	v_pk_add_f32 v[58:59], v[58:59], v[62:63]
	v_lshlrev_b32_e32 v62, 16, v2
	v_and_b32_e32 v63, 0xffff0000, v2
	v_pk_add_f32 v[60:61], v[60:61], v[0:1]
	v_lshlrev_b32_e32 v0, 16, v3
	v_and_b32_e32 v1, 0xffff0000, v3
	v_pk_add_f32 v[4:5], v[4:5], v[62:63]
	v_pk_add_f32 v[6:7], v[6:7], v[0:1]
	v_cvt_pk_bf16_f32 v0, v58, v59
	v_cvt_pk_bf16_f32 v1, v60, v61
	v_cvt_pk_bf16_f32 v2, v4, v5
	v_cvt_pk_bf16_f32 v3, v6, v7
	s_waitcnt vmcnt(7)
	s_nop 1
	v_mfma_f32_16x16x32_bf16 v[50:53], v[70:73], v[0:3], v[50:53]
	s_waitcnt vmcnt(6)
	v_mfma_f32_16x16x32_bf16 v[38:41], v[74:77], v[0:3], v[38:41]
	s_waitcnt vmcnt(5)
	v_mfma_f32_16x16x32_bf16 v[30:33], v[78:81], v[0:3], v[30:33]
	s_waitcnt vmcnt(4)
	v_mfma_f32_16x16x32_bf16 v[26:29], v[82:85], v[0:3], v[26:29]
	s_waitcnt vmcnt(3)
	v_mfma_f32_16x16x32_bf16 v[22:25], v[86:89], v[0:3], v[22:25]
	s_waitcnt vmcnt(2)
	v_mfma_f32_16x16x32_bf16 v[18:21], v[140:143], v[0:3], v[18:21]
	s_waitcnt vmcnt(1)
	v_mfma_f32_16x16x32_bf16 v[14:17], v[144:147], v[0:3], v[14:17]
	s_waitcnt vmcnt(0)
	v_mfma_f32_16x16x32_bf16 v[10:13], v[170:173], v[0:3], v[10:13]
.LBB0_1864:
	s_andn2_b64 vcc, exec, s[38:39]
	s_cbranch_vccnz .LBB0_1842
	v_and_b32_e32 v0, 1, v150
	v_lshlrev_b32_e32 v0, 2, v0
	v_sub_u32_e32 v1, 4, v0
	v_add_u32_e32 v121, s77, v155
	v_add3_u32 v123, s77, v156, v0
	v_add3_u32 v89, s77, v156, v1
	ds_read_b128 v[58:61], v121 offset:24576
	ds_read_b128 v[62:65], v121 offset:16384
	ds_read_b32 v82, v123 offset:40960
	ds_read_b32 v83, v89 offset:40960
	ds_read_b128 v[70:73], v121 offset:8192
	ds_read_b128 v[74:77], v121 offset:32768
	ds_read_b128 v[78:81], v121 offset:0
	s_waitcnt lgkmcnt(6)
	v_pk_mul_f32 v[84:85], v[54:55], v[58:59] op_sel_hi:[1,0]
	v_pk_fma_f32 v[84:85], v[56:57], v[58:59], v[84:85] op_sel:[0,1,0]
	v_pk_fma_f32 v[84:85], v[66:67], v[60:61], v[84:85] op_sel_hi:[1,0,1]
	v_pk_fma_f32 v[84:85], v[68:69], v[60:61], v[84:85] op_sel:[0,1,0]
	ds_read_b128 v[58:61], v121 offset:24832
	s_waitcnt lgkmcnt(4)
	v_pk_mul_f32 v[140:141], v[82:83], v[62:63] op_sel_hi:[1,0]
	v_add_f32_dpp v86, v85, v84 quad_perm:[1,0,3,2] row_mask:0xf bank_mask:0xf bound_ctrl:1
	v_pk_mul_f32 v[142:143], v[82:83], v[62:63] op_sel:[0,1]
	v_pk_mul_f32 v[144:145], v[82:83], v[64:65] op_sel_hi:[1,0]
	v_add_f32_dpp v86, v86, v86 quad_perm:[2,3,0,1] row_mask:0xf bank_mask:0xf bound_ctrl:1
	v_pk_mul_f32 v[146:147], v[82:83], v[64:65] op_sel:[0,1]
	ds_read_b128 v[62:65], v121 offset:16640
	ds_read_b32 v82, v123 offset:41088
	ds_read_b32 v83, v89 offset:41088
	s_waitcnt lgkmcnt(6)
	v_pk_fma_f32 v[140:141], v[54:55], v[70:71], v[140:141] op_sel_hi:[1,0,1]
	v_add_f32_dpp v86, v86, v86 row_ror:4 row_mask:0xf bank_mask:0xf bound_ctrl:1
	v_pk_fma_f32 v[142:143], v[56:57], v[70:71], v[142:143] op_sel:[0,1,0]
	v_pk_fma_f32 v[144:145], v[66:67], v[72:73], v[144:145] op_sel_hi:[1,0,1]
	v_add_f32_dpp v86, v86, v86 row_ror:8 row_mask:0xf bank_mask:0xf bound_ctrl:1
	v_pk_fma_f32 v[146:147], v[68:69], v[72:73], v[146:147] op_sel:[0,1,0]
	ds_read_b128 v[70:73], v121 offset:8448
	v_mov_b32_dpp v87, v86 quad_perm:[1,0,3,2] row_mask:0xf bank_mask:0xf bound_ctrl:1
	s_waitcnt lgkmcnt(6)
	v_pk_fma_f32 v[54:55], v[86:87], v[74:75], v[140:141] op_sel_hi:[1,0,1]
	v_pk_fma_f32 v[56:57], v[86:87], v[74:75], v[142:143] op_sel:[0,1,0]
	v_pk_fma_f32 v[66:67], v[86:87], v[76:77], v[144:145] op_sel_hi:[1,0,1]
	v_pk_fma_f32 v[68:69], v[86:87], v[76:77], v[146:147] op_sel:[0,1,0]
	ds_read_b128 v[74:77], v121 offset:33024
	s_waitcnt lgkmcnt(6)
	v_pk_mul_f32 v[148:149], v[54:55], v[78:79] op_sel_hi:[1,0]
	v_pk_fma_f32 v[148:149], v[56:57], v[78:79], v[148:149] op_sel:[0,1,0]
	v_pk_fma_f32 v[148:149], v[66:67], v[80:81], v[148:149] op_sel_hi:[1,0,1]
	v_pk_fma_f32 v[148:149], v[68:69], v[80:81], v[148:149] op_sel:[0,1,0]
	ds_read_b128 v[78:81], v121 offset:256
	s_waitcnt lgkmcnt(6)
	v_pk_mul_f32 v[84:85], v[54:55], v[58:59] op_sel_hi:[1,0]
	v_pk_fma_f32 v[84:85], v[56:57], v[58:59], v[84:85] op_sel:[0,1,0]
	v_pk_fma_f32 v[84:85], v[66:67], v[60:61], v[84:85] op_sel_hi:[1,0,1]
	v_pk_fma_f32 v[84:85], v[68:69], v[60:61], v[84:85] op_sel:[0,1,0]
	ds_read_b128 v[58:61], v121 offset:25088
	v_add_f32_dpp v88, v149, v148 quad_perm:[1,0,3,2] row_mask:0xf bank_mask:0xf bound_ctrl:1
	s_waitcnt lgkmcnt(4)
	v_pk_mul_f32 v[140:141], v[82:83], v[62:63] op_sel_hi:[1,0]
	v_add_f32_dpp v86, v85, v84 quad_perm:[1,0,3,2] row_mask:0xf bank_mask:0xf bound_ctrl:1
	v_pk_mul_f32 v[142:143], v[82:83], v[62:63] op_sel:[0,1]
	v_add_f32_dpp v88, v88, v88 quad_perm:[2,3,0,1] row_mask:0xf bank_mask:0xf bound_ctrl:1
	v_pk_mul_f32 v[144:145], v[82:83], v[64:65] op_sel_hi:[1,0]
	v_add_f32_dpp v86, v86, v86 quad_perm:[2,3,0,1] row_mask:0xf bank_mask:0xf bound_ctrl:1
	v_pk_mul_f32 v[146:147], v[82:83], v[64:65] op_sel:[0,1]
	ds_read_b128 v[62:65], v121 offset:16896
	ds_read_b32 v82, v123 offset:41216
	ds_read_b32 v83, v89 offset:41216
	v_add_f32_dpp v88, v88, v88 row_ror:4 row_mask:0xf bank_mask:0xf bound_ctrl:1
	s_waitcnt lgkmcnt(6)
	v_pk_fma_f32 v[140:141], v[54:55], v[70:71], v[140:141] op_sel_hi:[1,0,1]
	v_add_f32_dpp v86, v86, v86 row_ror:4 row_mask:0xf bank_mask:0xf bound_ctrl:1
	v_pk_fma_f32 v[142:143], v[56:57], v[70:71], v[142:143] op_sel:[0,1,0]
	v_add_f32_dpp v88, v88, v88 row_ror:8 row_mask:0xf bank_mask:0xf bound_ctrl:1
	v_pk_fma_f32 v[144:145], v[66:67], v[72:73], v[144:145] op_sel_hi:[1,0,1]
	v_add_f32_dpp v86, v86, v86 row_ror:8 row_mask:0xf bank_mask:0xf bound_ctrl:1
	v_pk_fma_f32 v[146:147], v[68:69], v[72:73], v[146:147] op_sel:[0,1,0]
	ds_read_b128 v[70:73], v121 offset:8704
	ds_write_b32 v123, v88 offset:45056
	v_mov_b32_dpp v87, v86 quad_perm:[1,0,3,2] row_mask:0xf bank_mask:0xf bound_ctrl:1
	s_waitcnt lgkmcnt(7)
	v_pk_fma_f32 v[54:55], v[86:87], v[74:75], v[140:141] op_sel_hi:[1,0,1]
	v_pk_fma_f32 v[56:57], v[86:87], v[74:75], v[142:143] op_sel:[0,1,0]
	v_pk_fma_f32 v[66:67], v[86:87], v[76:77], v[144:145] op_sel_hi:[1,0,1]
	v_pk_fma_f32 v[68:69], v[86:87], v[76:77], v[146:147] op_sel:[0,1,0]
	ds_read_b128 v[74:77], v121 offset:33280
	s_waitcnt lgkmcnt(7)
	v_pk_mul_f32 v[148:149], v[54:55], v[78:79] op_sel_hi:[1,0]
	v_pk_fma_f32 v[148:149], v[56:57], v[78:79], v[148:149] op_sel:[0,1,0]
	v_pk_fma_f32 v[148:149], v[66:67], v[80:81], v[148:149] op_sel_hi:[1,0,1]
	v_pk_fma_f32 v[148:149], v[68:69], v[80:81], v[148:149] op_sel:[0,1,0]
	ds_read_b128 v[78:81], v121 offset:512
	s_waitcnt lgkmcnt(7)
	v_pk_mul_f32 v[84:85], v[54:55], v[58:59] op_sel_hi:[1,0]
	v_pk_fma_f32 v[84:85], v[56:57], v[58:59], v[84:85] op_sel:[0,1,0]
	v_pk_fma_f32 v[84:85], v[66:67], v[60:61], v[84:85] op_sel_hi:[1,0,1]
	v_pk_fma_f32 v[84:85], v[68:69], v[60:61], v[84:85] op_sel:[0,1,0]
	ds_read_b128 v[58:61], v121 offset:25344
	v_add_f32_dpp v88, v149, v148 quad_perm:[1,0,3,2] row_mask:0xf bank_mask:0xf bound_ctrl:1
	s_waitcnt lgkmcnt(5)
	v_pk_mul_f32 v[140:141], v[82:83], v[62:63] op_sel_hi:[1,0]
	v_add_f32_dpp v86, v85, v84 quad_perm:[1,0,3,2] row_mask:0xf bank_mask:0xf bound_ctrl:1
	v_pk_mul_f32 v[142:143], v[82:83], v[62:63] op_sel:[0,1]
	v_add_f32_dpp v88, v88, v88 quad_perm:[2,3,0,1] row_mask:0xf bank_mask:0xf bound_ctrl:1
	v_pk_mul_f32 v[144:145], v[82:83], v[64:65] op_sel_hi:[1,0]
	v_add_f32_dpp v86, v86, v86 quad_perm:[2,3,0,1] row_mask:0xf bank_mask:0xf bound_ctrl:1
	v_pk_mul_f32 v[146:147], v[82:83], v[64:65] op_sel:[0,1]
	ds_read_b128 v[62:65], v121 offset:17152
	ds_read_b32 v82, v123 offset:41344
	ds_read_b32 v83, v89 offset:41344
	v_add_f32_dpp v88, v88, v88 row_ror:4 row_mask:0xf bank_mask:0xf bound_ctrl:1
	s_waitcnt lgkmcnt(7)
	v_pk_fma_f32 v[140:141], v[54:55], v[70:71], v[140:141] op_sel_hi:[1,0,1]
	v_add_f32_dpp v86, v86, v86 row_ror:4 row_mask:0xf bank_mask:0xf bound_ctrl:1
	v_pk_fma_f32 v[142:143], v[56:57], v[70:71], v[142:143] op_sel:[0,1,0]
	v_add_f32_dpp v88, v88, v88 row_ror:8 row_mask:0xf bank_mask:0xf bound_ctrl:1
	v_pk_fma_f32 v[144:145], v[66:67], v[72:73], v[144:145] op_sel_hi:[1,0,1]
	v_add_f32_dpp v86, v86, v86 row_ror:8 row_mask:0xf bank_mask:0xf bound_ctrl:1
	v_pk_fma_f32 v[146:147], v[68:69], v[72:73], v[146:147] op_sel:[0,1,0]
	ds_read_b128 v[70:73], v121 offset:8960
	ds_write_b32 v123, v88 offset:45184
	v_mov_b32_dpp v87, v86 quad_perm:[1,0,3,2] row_mask:0xf bank_mask:0xf bound_ctrl:1
	s_waitcnt lgkmcnt(7)
	v_pk_fma_f32 v[54:55], v[86:87], v[74:75], v[140:141] op_sel_hi:[1,0,1]
	v_pk_fma_f32 v[56:57], v[86:87], v[74:75], v[142:143] op_sel:[0,1,0]
	v_pk_fma_f32 v[66:67], v[86:87], v[76:77], v[144:145] op_sel_hi:[1,0,1]
	v_pk_fma_f32 v[68:69], v[86:87], v[76:77], v[146:147] op_sel:[0,1,0]
	ds_read_b128 v[74:77], v121 offset:33536
	s_waitcnt lgkmcnt(7)
	v_pk_mul_f32 v[148:149], v[54:55], v[78:79] op_sel_hi:[1,0]
	v_pk_fma_f32 v[148:149], v[56:57], v[78:79], v[148:149] op_sel:[0,1,0]
	v_pk_fma_f32 v[148:149], v[66:67], v[80:81], v[148:149] op_sel_hi:[1,0,1]
	v_pk_fma_f32 v[148:149], v[68:69], v[80:81], v[148:149] op_sel:[0,1,0]
	ds_read_b128 v[78:81], v121 offset:768
	s_waitcnt lgkmcnt(7)
	v_pk_mul_f32 v[84:85], v[54:55], v[58:59] op_sel_hi:[1,0]
	v_pk_fma_f32 v[84:85], v[56:57], v[58:59], v[84:85] op_sel:[0,1,0]
	v_pk_fma_f32 v[84:85], v[66:67], v[60:61], v[84:85] op_sel_hi:[1,0,1]
	v_pk_fma_f32 v[84:85], v[68:69], v[60:61], v[84:85] op_sel:[0,1,0]
	ds_read_b128 v[58:61], v121 offset:25600
	v_add_f32_dpp v88, v149, v148 quad_perm:[1,0,3,2] row_mask:0xf bank_mask:0xf bound_ctrl:1
	s_waitcnt lgkmcnt(5)
	v_pk_mul_f32 v[140:141], v[82:83], v[62:63] op_sel_hi:[1,0]
	v_add_f32_dpp v86, v85, v84 quad_perm:[1,0,3,2] row_mask:0xf bank_mask:0xf bound_ctrl:1
	v_pk_mul_f32 v[142:143], v[82:83], v[62:63] op_sel:[0,1]
	v_add_f32_dpp v88, v88, v88 quad_perm:[2,3,0,1] row_mask:0xf bank_mask:0xf bound_ctrl:1
	v_pk_mul_f32 v[144:145], v[82:83], v[64:65] op_sel_hi:[1,0]
	v_add_f32_dpp v86, v86, v86 quad_perm:[2,3,0,1] row_mask:0xf bank_mask:0xf bound_ctrl:1
	v_pk_mul_f32 v[146:147], v[82:83], v[64:65] op_sel:[0,1]
	ds_read_b128 v[62:65], v121 offset:17408
	ds_read_b32 v82, v123 offset:41472
	ds_read_b32 v83, v89 offset:41472
	v_add_f32_dpp v88, v88, v88 row_ror:4 row_mask:0xf bank_mask:0xf bound_ctrl:1
	s_waitcnt lgkmcnt(7)
	v_pk_fma_f32 v[140:141], v[54:55], v[70:71], v[140:141] op_sel_hi:[1,0,1]
	v_add_f32_dpp v86, v86, v86 row_ror:4 row_mask:0xf bank_mask:0xf bound_ctrl:1
	v_pk_fma_f32 v[142:143], v[56:57], v[70:71], v[142:143] op_sel:[0,1,0]
	v_add_f32_dpp v88, v88, v88 row_ror:8 row_mask:0xf bank_mask:0xf bound_ctrl:1
	v_pk_fma_f32 v[144:145], v[66:67], v[72:73], v[144:145] op_sel_hi:[1,0,1]
	v_add_f32_dpp v86, v86, v86 row_ror:8 row_mask:0xf bank_mask:0xf bound_ctrl:1
	v_pk_fma_f32 v[146:147], v[68:69], v[72:73], v[146:147] op_sel:[0,1,0]
	ds_read_b128 v[70:73], v121 offset:9216
	ds_write_b32 v123, v88 offset:45312
	v_mov_b32_dpp v87, v86 quad_perm:[1,0,3,2] row_mask:0xf bank_mask:0xf bound_ctrl:1
	s_waitcnt lgkmcnt(7)
	v_pk_fma_f32 v[54:55], v[86:87], v[74:75], v[140:141] op_sel_hi:[1,0,1]
	v_pk_fma_f32 v[56:57], v[86:87], v[74:75], v[142:143] op_sel:[0,1,0]
	v_pk_fma_f32 v[66:67], v[86:87], v[76:77], v[144:145] op_sel_hi:[1,0,1]
	v_pk_fma_f32 v[68:69], v[86:87], v[76:77], v[146:147] op_sel:[0,1,0]
	ds_read_b128 v[74:77], v121 offset:33792
	s_waitcnt lgkmcnt(7)
	v_pk_mul_f32 v[148:149], v[54:55], v[78:79] op_sel_hi:[1,0]
	v_pk_fma_f32 v[148:149], v[56:57], v[78:79], v[148:149] op_sel:[0,1,0]
	v_pk_fma_f32 v[148:149], v[66:67], v[80:81], v[148:149] op_sel_hi:[1,0,1]
	v_pk_fma_f32 v[148:149], v[68:69], v[80:81], v[148:149] op_sel:[0,1,0]
	ds_read_b128 v[78:81], v121 offset:1024
	s_waitcnt lgkmcnt(7)
	v_pk_mul_f32 v[84:85], v[54:55], v[58:59] op_sel_hi:[1,0]
	v_pk_fma_f32 v[84:85], v[56:57], v[58:59], v[84:85] op_sel:[0,1,0]
	v_pk_fma_f32 v[84:85], v[66:67], v[60:61], v[84:85] op_sel_hi:[1,0,1]
	v_pk_fma_f32 v[84:85], v[68:69], v[60:61], v[84:85] op_sel:[0,1,0]
	ds_read_b128 v[58:61], v121 offset:25856
	v_add_f32_dpp v88, v149, v148 quad_perm:[1,0,3,2] row_mask:0xf bank_mask:0xf bound_ctrl:1
	s_waitcnt lgkmcnt(5)
	v_pk_mul_f32 v[140:141], v[82:83], v[62:63] op_sel_hi:[1,0]
	v_add_f32_dpp v86, v85, v84 quad_perm:[1,0,3,2] row_mask:0xf bank_mask:0xf bound_ctrl:1
	v_pk_mul_f32 v[142:143], v[82:83], v[62:63] op_sel:[0,1]
	v_add_f32_dpp v88, v88, v88 quad_perm:[2,3,0,1] row_mask:0xf bank_mask:0xf bound_ctrl:1
	v_pk_mul_f32 v[144:145], v[82:83], v[64:65] op_sel_hi:[1,0]
	v_add_f32_dpp v86, v86, v86 quad_perm:[2,3,0,1] row_mask:0xf bank_mask:0xf bound_ctrl:1
	v_pk_mul_f32 v[146:147], v[82:83], v[64:65] op_sel:[0,1]
	ds_read_b128 v[62:65], v121 offset:17664
	ds_read_b32 v82, v123 offset:41600
	ds_read_b32 v83, v89 offset:41600
	v_add_f32_dpp v88, v88, v88 row_ror:4 row_mask:0xf bank_mask:0xf bound_ctrl:1
	s_waitcnt lgkmcnt(7)
	v_pk_fma_f32 v[140:141], v[54:55], v[70:71], v[140:141] op_sel_hi:[1,0,1]
	v_add_f32_dpp v86, v86, v86 row_ror:4 row_mask:0xf bank_mask:0xf bound_ctrl:1
	v_pk_fma_f32 v[142:143], v[56:57], v[70:71], v[142:143] op_sel:[0,1,0]
	v_add_f32_dpp v88, v88, v88 row_ror:8 row_mask:0xf bank_mask:0xf bound_ctrl:1
	v_pk_fma_f32 v[144:145], v[66:67], v[72:73], v[144:145] op_sel_hi:[1,0,1]
	v_add_f32_dpp v86, v86, v86 row_ror:8 row_mask:0xf bank_mask:0xf bound_ctrl:1
	v_pk_fma_f32 v[146:147], v[68:69], v[72:73], v[146:147] op_sel:[0,1,0]
	ds_read_b128 v[70:73], v121 offset:9472
	ds_write_b32 v123, v88 offset:45440
	v_mov_b32_dpp v87, v86 quad_perm:[1,0,3,2] row_mask:0xf bank_mask:0xf bound_ctrl:1
	s_waitcnt lgkmcnt(7)
	v_pk_fma_f32 v[54:55], v[86:87], v[74:75], v[140:141] op_sel_hi:[1,0,1]
	v_pk_fma_f32 v[56:57], v[86:87], v[74:75], v[142:143] op_sel:[0,1,0]
	v_pk_fma_f32 v[66:67], v[86:87], v[76:77], v[144:145] op_sel_hi:[1,0,1]
	v_pk_fma_f32 v[68:69], v[86:87], v[76:77], v[146:147] op_sel:[0,1,0]
	ds_read_b128 v[74:77], v121 offset:34048
	s_waitcnt lgkmcnt(7)
	v_pk_mul_f32 v[148:149], v[54:55], v[78:79] op_sel_hi:[1,0]
	v_pk_fma_f32 v[148:149], v[56:57], v[78:79], v[148:149] op_sel:[0,1,0]
	v_pk_fma_f32 v[148:149], v[66:67], v[80:81], v[148:149] op_sel_hi:[1,0,1]
	v_pk_fma_f32 v[148:149], v[68:69], v[80:81], v[148:149] op_sel:[0,1,0]
	ds_read_b128 v[78:81], v121 offset:1280
	s_waitcnt lgkmcnt(7)
	v_pk_mul_f32 v[84:85], v[54:55], v[58:59] op_sel_hi:[1,0]
	v_pk_fma_f32 v[84:85], v[56:57], v[58:59], v[84:85] op_sel:[0,1,0]
	v_pk_fma_f32 v[84:85], v[66:67], v[60:61], v[84:85] op_sel_hi:[1,0,1]
	v_pk_fma_f32 v[84:85], v[68:69], v[60:61], v[84:85] op_sel:[0,1,0]
	ds_read_b128 v[58:61], v121 offset:26112
	v_add_f32_dpp v88, v149, v148 quad_perm:[1,0,3,2] row_mask:0xf bank_mask:0xf bound_ctrl:1
	s_waitcnt lgkmcnt(5)
	v_pk_mul_f32 v[140:141], v[82:83], v[62:63] op_sel_hi:[1,0]
	v_add_f32_dpp v86, v85, v84 quad_perm:[1,0,3,2] row_mask:0xf bank_mask:0xf bound_ctrl:1
	v_pk_mul_f32 v[142:143], v[82:83], v[62:63] op_sel:[0,1]
	v_add_f32_dpp v88, v88, v88 quad_perm:[2,3,0,1] row_mask:0xf bank_mask:0xf bound_ctrl:1
	v_pk_mul_f32 v[144:145], v[82:83], v[64:65] op_sel_hi:[1,0]
	v_add_f32_dpp v86, v86, v86 quad_perm:[2,3,0,1] row_mask:0xf bank_mask:0xf bound_ctrl:1
	v_pk_mul_f32 v[146:147], v[82:83], v[64:65] op_sel:[0,1]
	ds_read_b128 v[62:65], v121 offset:17920
	ds_read_b32 v82, v123 offset:41728
	ds_read_b32 v83, v89 offset:41728
	v_add_f32_dpp v88, v88, v88 row_ror:4 row_mask:0xf bank_mask:0xf bound_ctrl:1
	s_waitcnt lgkmcnt(7)
	v_pk_fma_f32 v[140:141], v[54:55], v[70:71], v[140:141] op_sel_hi:[1,0,1]
	v_add_f32_dpp v86, v86, v86 row_ror:4 row_mask:0xf bank_mask:0xf bound_ctrl:1
	v_pk_fma_f32 v[142:143], v[56:57], v[70:71], v[142:143] op_sel:[0,1,0]
	v_add_f32_dpp v88, v88, v88 row_ror:8 row_mask:0xf bank_mask:0xf bound_ctrl:1
	v_pk_fma_f32 v[144:145], v[66:67], v[72:73], v[144:145] op_sel_hi:[1,0,1]
	v_add_f32_dpp v86, v86, v86 row_ror:8 row_mask:0xf bank_mask:0xf bound_ctrl:1
	v_pk_fma_f32 v[146:147], v[68:69], v[72:73], v[146:147] op_sel:[0,1,0]
	ds_read_b128 v[70:73], v121 offset:9728
	ds_write_b32 v123, v88 offset:45568
	v_mov_b32_dpp v87, v86 quad_perm:[1,0,3,2] row_mask:0xf bank_mask:0xf bound_ctrl:1
	s_waitcnt lgkmcnt(7)
	v_pk_fma_f32 v[54:55], v[86:87], v[74:75], v[140:141] op_sel_hi:[1,0,1]
	v_pk_fma_f32 v[56:57], v[86:87], v[74:75], v[142:143] op_sel:[0,1,0]
	v_pk_fma_f32 v[66:67], v[86:87], v[76:77], v[144:145] op_sel_hi:[1,0,1]
	v_pk_fma_f32 v[68:69], v[86:87], v[76:77], v[146:147] op_sel:[0,1,0]
	ds_read_b128 v[74:77], v121 offset:34304
	s_waitcnt lgkmcnt(7)
	v_pk_mul_f32 v[148:149], v[54:55], v[78:79] op_sel_hi:[1,0]
	v_pk_fma_f32 v[148:149], v[56:57], v[78:79], v[148:149] op_sel:[0,1,0]
	v_pk_fma_f32 v[148:149], v[66:67], v[80:81], v[148:149] op_sel_hi:[1,0,1]
	v_pk_fma_f32 v[148:149], v[68:69], v[80:81], v[148:149] op_sel:[0,1,0]
	ds_read_b128 v[78:81], v121 offset:1536
	s_waitcnt lgkmcnt(7)
	v_pk_mul_f32 v[84:85], v[54:55], v[58:59] op_sel_hi:[1,0]
	v_pk_fma_f32 v[84:85], v[56:57], v[58:59], v[84:85] op_sel:[0,1,0]
	v_pk_fma_f32 v[84:85], v[66:67], v[60:61], v[84:85] op_sel_hi:[1,0,1]
	v_pk_fma_f32 v[84:85], v[68:69], v[60:61], v[84:85] op_sel:[0,1,0]
	ds_read_b128 v[58:61], v121 offset:26368
	v_add_f32_dpp v88, v149, v148 quad_perm:[1,0,3,2] row_mask:0xf bank_mask:0xf bound_ctrl:1
	s_waitcnt lgkmcnt(5)
	v_pk_mul_f32 v[140:141], v[82:83], v[62:63] op_sel_hi:[1,0]
	v_add_f32_dpp v86, v85, v84 quad_perm:[1,0,3,2] row_mask:0xf bank_mask:0xf bound_ctrl:1
	v_pk_mul_f32 v[142:143], v[82:83], v[62:63] op_sel:[0,1]
	v_add_f32_dpp v88, v88, v88 quad_perm:[2,3,0,1] row_mask:0xf bank_mask:0xf bound_ctrl:1
	v_pk_mul_f32 v[144:145], v[82:83], v[64:65] op_sel_hi:[1,0]
	v_add_f32_dpp v86, v86, v86 quad_perm:[2,3,0,1] row_mask:0xf bank_mask:0xf bound_ctrl:1
	v_pk_mul_f32 v[146:147], v[82:83], v[64:65] op_sel:[0,1]
	ds_read_b128 v[62:65], v121 offset:18176
	ds_read_b32 v82, v123 offset:41856
	ds_read_b32 v83, v89 offset:41856
	v_add_f32_dpp v88, v88, v88 row_ror:4 row_mask:0xf bank_mask:0xf bound_ctrl:1
	s_waitcnt lgkmcnt(7)
	v_pk_fma_f32 v[140:141], v[54:55], v[70:71], v[140:141] op_sel_hi:[1,0,1]
	v_add_f32_dpp v86, v86, v86 row_ror:4 row_mask:0xf bank_mask:0xf bound_ctrl:1
	v_pk_fma_f32 v[142:143], v[56:57], v[70:71], v[142:143] op_sel:[0,1,0]
	v_add_f32_dpp v88, v88, v88 row_ror:8 row_mask:0xf bank_mask:0xf bound_ctrl:1
	v_pk_fma_f32 v[144:145], v[66:67], v[72:73], v[144:145] op_sel_hi:[1,0,1]
	v_add_f32_dpp v86, v86, v86 row_ror:8 row_mask:0xf bank_mask:0xf bound_ctrl:1
	v_pk_fma_f32 v[146:147], v[68:69], v[72:73], v[146:147] op_sel:[0,1,0]
	ds_read_b128 v[70:73], v121 offset:9984
	ds_write_b32 v123, v88 offset:45696
	v_mov_b32_dpp v87, v86 quad_perm:[1,0,3,2] row_mask:0xf bank_mask:0xf bound_ctrl:1
	s_waitcnt lgkmcnt(7)
	v_pk_fma_f32 v[54:55], v[86:87], v[74:75], v[140:141] op_sel_hi:[1,0,1]
	v_pk_fma_f32 v[56:57], v[86:87], v[74:75], v[142:143] op_sel:[0,1,0]
	v_pk_fma_f32 v[66:67], v[86:87], v[76:77], v[144:145] op_sel_hi:[1,0,1]
	v_pk_fma_f32 v[68:69], v[86:87], v[76:77], v[146:147] op_sel:[0,1,0]
	ds_read_b128 v[74:77], v121 offset:34560
	s_waitcnt lgkmcnt(7)
	v_pk_mul_f32 v[148:149], v[54:55], v[78:79] op_sel_hi:[1,0]
	v_pk_fma_f32 v[148:149], v[56:57], v[78:79], v[148:149] op_sel:[0,1,0]
	v_pk_fma_f32 v[148:149], v[66:67], v[80:81], v[148:149] op_sel_hi:[1,0,1]
	v_pk_fma_f32 v[148:149], v[68:69], v[80:81], v[148:149] op_sel:[0,1,0]
	ds_read_b128 v[78:81], v121 offset:1792
	s_waitcnt lgkmcnt(7)
	v_pk_mul_f32 v[84:85], v[54:55], v[58:59] op_sel_hi:[1,0]
	v_pk_fma_f32 v[84:85], v[56:57], v[58:59], v[84:85] op_sel:[0,1,0]
	v_pk_fma_f32 v[84:85], v[66:67], v[60:61], v[84:85] op_sel_hi:[1,0,1]
	v_pk_fma_f32 v[84:85], v[68:69], v[60:61], v[84:85] op_sel:[0,1,0]
	ds_read_b128 v[58:61], v121 offset:26624
	v_add_f32_dpp v88, v149, v148 quad_perm:[1,0,3,2] row_mask:0xf bank_mask:0xf bound_ctrl:1
	s_waitcnt lgkmcnt(5)
	v_pk_mul_f32 v[140:141], v[82:83], v[62:63] op_sel_hi:[1,0]
	v_add_f32_dpp v86, v85, v84 quad_perm:[1,0,3,2] row_mask:0xf bank_mask:0xf bound_ctrl:1
	v_pk_mul_f32 v[142:143], v[82:83], v[62:63] op_sel:[0,1]
	v_add_f32_dpp v88, v88, v88 quad_perm:[2,3,0,1] row_mask:0xf bank_mask:0xf bound_ctrl:1
	v_pk_mul_f32 v[144:145], v[82:83], v[64:65] op_sel_hi:[1,0]
	v_add_f32_dpp v86, v86, v86 quad_perm:[2,3,0,1] row_mask:0xf bank_mask:0xf bound_ctrl:1
	v_pk_mul_f32 v[146:147], v[82:83], v[64:65] op_sel:[0,1]
	ds_read_b128 v[62:65], v121 offset:18432
	ds_read_b32 v82, v123 offset:41984
	ds_read_b32 v83, v89 offset:41984
	v_add_f32_dpp v88, v88, v88 row_ror:4 row_mask:0xf bank_mask:0xf bound_ctrl:1
	s_waitcnt lgkmcnt(7)
	v_pk_fma_f32 v[140:141], v[54:55], v[70:71], v[140:141] op_sel_hi:[1,0,1]
	v_add_f32_dpp v86, v86, v86 row_ror:4 row_mask:0xf bank_mask:0xf bound_ctrl:1
	v_pk_fma_f32 v[142:143], v[56:57], v[70:71], v[142:143] op_sel:[0,1,0]
	v_add_f32_dpp v88, v88, v88 row_ror:8 row_mask:0xf bank_mask:0xf bound_ctrl:1
	v_pk_fma_f32 v[144:145], v[66:67], v[72:73], v[144:145] op_sel_hi:[1,0,1]
	v_add_f32_dpp v86, v86, v86 row_ror:8 row_mask:0xf bank_mask:0xf bound_ctrl:1
	v_pk_fma_f32 v[146:147], v[68:69], v[72:73], v[146:147] op_sel:[0,1,0]
	ds_read_b128 v[70:73], v121 offset:10240
	ds_write_b32 v123, v88 offset:45824
	v_mov_b32_dpp v87, v86 quad_perm:[1,0,3,2] row_mask:0xf bank_mask:0xf bound_ctrl:1
	s_waitcnt lgkmcnt(7)
	v_pk_fma_f32 v[54:55], v[86:87], v[74:75], v[140:141] op_sel_hi:[1,0,1]
	v_pk_fma_f32 v[56:57], v[86:87], v[74:75], v[142:143] op_sel:[0,1,0]
	v_pk_fma_f32 v[66:67], v[86:87], v[76:77], v[144:145] op_sel_hi:[1,0,1]
	v_pk_fma_f32 v[68:69], v[86:87], v[76:77], v[146:147] op_sel:[0,1,0]
	ds_read_b128 v[74:77], v121 offset:34816
	s_waitcnt lgkmcnt(7)
	v_pk_mul_f32 v[148:149], v[54:55], v[78:79] op_sel_hi:[1,0]
	v_pk_fma_f32 v[148:149], v[56:57], v[78:79], v[148:149] op_sel:[0,1,0]
	v_pk_fma_f32 v[148:149], v[66:67], v[80:81], v[148:149] op_sel_hi:[1,0,1]
	v_pk_fma_f32 v[148:149], v[68:69], v[80:81], v[148:149] op_sel:[0,1,0]
	ds_read_b128 v[78:81], v121 offset:2048
	s_waitcnt lgkmcnt(7)
	v_pk_mul_f32 v[84:85], v[54:55], v[58:59] op_sel_hi:[1,0]
	v_pk_fma_f32 v[84:85], v[56:57], v[58:59], v[84:85] op_sel:[0,1,0]
	v_pk_fma_f32 v[84:85], v[66:67], v[60:61], v[84:85] op_sel_hi:[1,0,1]
	v_pk_fma_f32 v[84:85], v[68:69], v[60:61], v[84:85] op_sel:[0,1,0]
	ds_read_b128 v[58:61], v121 offset:26880
	v_add_f32_dpp v88, v149, v148 quad_perm:[1,0,3,2] row_mask:0xf bank_mask:0xf bound_ctrl:1
	s_waitcnt lgkmcnt(5)
	v_pk_mul_f32 v[140:141], v[82:83], v[62:63] op_sel_hi:[1,0]
	v_add_f32_dpp v86, v85, v84 quad_perm:[1,0,3,2] row_mask:0xf bank_mask:0xf bound_ctrl:1
	v_pk_mul_f32 v[142:143], v[82:83], v[62:63] op_sel:[0,1]
	v_add_f32_dpp v88, v88, v88 quad_perm:[2,3,0,1] row_mask:0xf bank_mask:0xf bound_ctrl:1
	v_pk_mul_f32 v[144:145], v[82:83], v[64:65] op_sel_hi:[1,0]
	v_add_f32_dpp v86, v86, v86 quad_perm:[2,3,0,1] row_mask:0xf bank_mask:0xf bound_ctrl:1
	v_pk_mul_f32 v[146:147], v[82:83], v[64:65] op_sel:[0,1]
	ds_read_b128 v[62:65], v121 offset:18688
	ds_read_b32 v82, v123 offset:42112
	ds_read_b32 v83, v89 offset:42112
	v_add_f32_dpp v88, v88, v88 row_ror:4 row_mask:0xf bank_mask:0xf bound_ctrl:1
	s_waitcnt lgkmcnt(7)
	v_pk_fma_f32 v[140:141], v[54:55], v[70:71], v[140:141] op_sel_hi:[1,0,1]
	v_add_f32_dpp v86, v86, v86 row_ror:4 row_mask:0xf bank_mask:0xf bound_ctrl:1
	v_pk_fma_f32 v[142:143], v[56:57], v[70:71], v[142:143] op_sel:[0,1,0]
	v_add_f32_dpp v88, v88, v88 row_ror:8 row_mask:0xf bank_mask:0xf bound_ctrl:1
	v_pk_fma_f32 v[144:145], v[66:67], v[72:73], v[144:145] op_sel_hi:[1,0,1]
	v_add_f32_dpp v86, v86, v86 row_ror:8 row_mask:0xf bank_mask:0xf bound_ctrl:1
	v_pk_fma_f32 v[146:147], v[68:69], v[72:73], v[146:147] op_sel:[0,1,0]
	ds_read_b128 v[70:73], v121 offset:10496
	ds_write_b32 v123, v88 offset:45952
	v_mov_b32_dpp v87, v86 quad_perm:[1,0,3,2] row_mask:0xf bank_mask:0xf bound_ctrl:1
	s_waitcnt lgkmcnt(7)
	v_pk_fma_f32 v[54:55], v[86:87], v[74:75], v[140:141] op_sel_hi:[1,0,1]
	v_pk_fma_f32 v[56:57], v[86:87], v[74:75], v[142:143] op_sel:[0,1,0]
	v_pk_fma_f32 v[66:67], v[86:87], v[76:77], v[144:145] op_sel_hi:[1,0,1]
	v_pk_fma_f32 v[68:69], v[86:87], v[76:77], v[146:147] op_sel:[0,1,0]
	ds_read_b128 v[74:77], v121 offset:35072
	s_waitcnt lgkmcnt(7)
	v_pk_mul_f32 v[148:149], v[54:55], v[78:79] op_sel_hi:[1,0]
	v_pk_fma_f32 v[148:149], v[56:57], v[78:79], v[148:149] op_sel:[0,1,0]
	v_pk_fma_f32 v[148:149], v[66:67], v[80:81], v[148:149] op_sel_hi:[1,0,1]
	v_pk_fma_f32 v[148:149], v[68:69], v[80:81], v[148:149] op_sel:[0,1,0]
	ds_read_b128 v[78:81], v121 offset:2304
	s_waitcnt lgkmcnt(7)
	v_pk_mul_f32 v[84:85], v[54:55], v[58:59] op_sel_hi:[1,0]
	v_pk_fma_f32 v[84:85], v[56:57], v[58:59], v[84:85] op_sel:[0,1,0]
	v_pk_fma_f32 v[84:85], v[66:67], v[60:61], v[84:85] op_sel_hi:[1,0,1]
	v_pk_fma_f32 v[84:85], v[68:69], v[60:61], v[84:85] op_sel:[0,1,0]
	ds_read_b128 v[58:61], v121 offset:27136
	v_add_f32_dpp v88, v149, v148 quad_perm:[1,0,3,2] row_mask:0xf bank_mask:0xf bound_ctrl:1
	s_waitcnt lgkmcnt(5)
	v_pk_mul_f32 v[140:141], v[82:83], v[62:63] op_sel_hi:[1,0]
	v_add_f32_dpp v86, v85, v84 quad_perm:[1,0,3,2] row_mask:0xf bank_mask:0xf bound_ctrl:1
	v_pk_mul_f32 v[142:143], v[82:83], v[62:63] op_sel:[0,1]
	v_add_f32_dpp v88, v88, v88 quad_perm:[2,3,0,1] row_mask:0xf bank_mask:0xf bound_ctrl:1
	v_pk_mul_f32 v[144:145], v[82:83], v[64:65] op_sel_hi:[1,0]
	v_add_f32_dpp v86, v86, v86 quad_perm:[2,3,0,1] row_mask:0xf bank_mask:0xf bound_ctrl:1
	v_pk_mul_f32 v[146:147], v[82:83], v[64:65] op_sel:[0,1]
	ds_read_b128 v[62:65], v121 offset:18944
	ds_read_b32 v82, v123 offset:42240
	ds_read_b32 v83, v89 offset:42240
	v_add_f32_dpp v88, v88, v88 row_ror:4 row_mask:0xf bank_mask:0xf bound_ctrl:1
	s_waitcnt lgkmcnt(7)
	v_pk_fma_f32 v[140:141], v[54:55], v[70:71], v[140:141] op_sel_hi:[1,0,1]
	v_add_f32_dpp v86, v86, v86 row_ror:4 row_mask:0xf bank_mask:0xf bound_ctrl:1
	v_pk_fma_f32 v[142:143], v[56:57], v[70:71], v[142:143] op_sel:[0,1,0]
	v_add_f32_dpp v88, v88, v88 row_ror:8 row_mask:0xf bank_mask:0xf bound_ctrl:1
	v_pk_fma_f32 v[144:145], v[66:67], v[72:73], v[144:145] op_sel_hi:[1,0,1]
	v_add_f32_dpp v86, v86, v86 row_ror:8 row_mask:0xf bank_mask:0xf bound_ctrl:1
	v_pk_fma_f32 v[146:147], v[68:69], v[72:73], v[146:147] op_sel:[0,1,0]
	ds_read_b128 v[70:73], v121 offset:10752
	ds_write_b32 v123, v88 offset:46080
	v_mov_b32_dpp v87, v86 quad_perm:[1,0,3,2] row_mask:0xf bank_mask:0xf bound_ctrl:1
	s_waitcnt lgkmcnt(7)
	v_pk_fma_f32 v[54:55], v[86:87], v[74:75], v[140:141] op_sel_hi:[1,0,1]
	v_pk_fma_f32 v[56:57], v[86:87], v[74:75], v[142:143] op_sel:[0,1,0]
	v_pk_fma_f32 v[66:67], v[86:87], v[76:77], v[144:145] op_sel_hi:[1,0,1]
	v_pk_fma_f32 v[68:69], v[86:87], v[76:77], v[146:147] op_sel:[0,1,0]
	ds_read_b128 v[74:77], v121 offset:35328
	s_waitcnt lgkmcnt(7)
	v_pk_mul_f32 v[148:149], v[54:55], v[78:79] op_sel_hi:[1,0]
	v_pk_fma_f32 v[148:149], v[56:57], v[78:79], v[148:149] op_sel:[0,1,0]
	v_pk_fma_f32 v[148:149], v[66:67], v[80:81], v[148:149] op_sel_hi:[1,0,1]
	v_pk_fma_f32 v[148:149], v[68:69], v[80:81], v[148:149] op_sel:[0,1,0]
	ds_read_b128 v[78:81], v121 offset:2560
	s_waitcnt lgkmcnt(7)
	v_pk_mul_f32 v[84:85], v[54:55], v[58:59] op_sel_hi:[1,0]
	v_pk_fma_f32 v[84:85], v[56:57], v[58:59], v[84:85] op_sel:[0,1,0]
	v_pk_fma_f32 v[84:85], v[66:67], v[60:61], v[84:85] op_sel_hi:[1,0,1]
	v_pk_fma_f32 v[84:85], v[68:69], v[60:61], v[84:85] op_sel:[0,1,0]
	ds_read_b128 v[58:61], v121 offset:27392
	v_add_f32_dpp v88, v149, v148 quad_perm:[1,0,3,2] row_mask:0xf bank_mask:0xf bound_ctrl:1
	s_waitcnt lgkmcnt(5)
	v_pk_mul_f32 v[140:141], v[82:83], v[62:63] op_sel_hi:[1,0]
	v_add_f32_dpp v86, v85, v84 quad_perm:[1,0,3,2] row_mask:0xf bank_mask:0xf bound_ctrl:1
	v_pk_mul_f32 v[142:143], v[82:83], v[62:63] op_sel:[0,1]
	v_add_f32_dpp v88, v88, v88 quad_perm:[2,3,0,1] row_mask:0xf bank_mask:0xf bound_ctrl:1
	v_pk_mul_f32 v[144:145], v[82:83], v[64:65] op_sel_hi:[1,0]
	v_add_f32_dpp v86, v86, v86 quad_perm:[2,3,0,1] row_mask:0xf bank_mask:0xf bound_ctrl:1
	v_pk_mul_f32 v[146:147], v[82:83], v[64:65] op_sel:[0,1]
	ds_read_b128 v[62:65], v121 offset:19200
	ds_read_b32 v82, v123 offset:42368
	ds_read_b32 v83, v89 offset:42368
	v_add_f32_dpp v88, v88, v88 row_ror:4 row_mask:0xf bank_mask:0xf bound_ctrl:1
	s_waitcnt lgkmcnt(7)
	v_pk_fma_f32 v[140:141], v[54:55], v[70:71], v[140:141] op_sel_hi:[1,0,1]
	v_add_f32_dpp v86, v86, v86 row_ror:4 row_mask:0xf bank_mask:0xf bound_ctrl:1
	v_pk_fma_f32 v[142:143], v[56:57], v[70:71], v[142:143] op_sel:[0,1,0]
	v_add_f32_dpp v88, v88, v88 row_ror:8 row_mask:0xf bank_mask:0xf bound_ctrl:1
	v_pk_fma_f32 v[144:145], v[66:67], v[72:73], v[144:145] op_sel_hi:[1,0,1]
	v_add_f32_dpp v86, v86, v86 row_ror:8 row_mask:0xf bank_mask:0xf bound_ctrl:1
	v_pk_fma_f32 v[146:147], v[68:69], v[72:73], v[146:147] op_sel:[0,1,0]
	ds_read_b128 v[70:73], v121 offset:11008
	ds_write_b32 v123, v88 offset:46208
	v_mov_b32_dpp v87, v86 quad_perm:[1,0,3,2] row_mask:0xf bank_mask:0xf bound_ctrl:1
	s_waitcnt lgkmcnt(7)
	v_pk_fma_f32 v[54:55], v[86:87], v[74:75], v[140:141] op_sel_hi:[1,0,1]
	v_pk_fma_f32 v[56:57], v[86:87], v[74:75], v[142:143] op_sel:[0,1,0]
	v_pk_fma_f32 v[66:67], v[86:87], v[76:77], v[144:145] op_sel_hi:[1,0,1]
	v_pk_fma_f32 v[68:69], v[86:87], v[76:77], v[146:147] op_sel:[0,1,0]
	ds_read_b128 v[74:77], v121 offset:35584
	s_waitcnt lgkmcnt(7)
	v_pk_mul_f32 v[148:149], v[54:55], v[78:79] op_sel_hi:[1,0]
	v_pk_fma_f32 v[148:149], v[56:57], v[78:79], v[148:149] op_sel:[0,1,0]
	v_pk_fma_f32 v[148:149], v[66:67], v[80:81], v[148:149] op_sel_hi:[1,0,1]
	v_pk_fma_f32 v[148:149], v[68:69], v[80:81], v[148:149] op_sel:[0,1,0]
	ds_read_b128 v[78:81], v121 offset:2816
	s_waitcnt lgkmcnt(7)
	v_pk_mul_f32 v[84:85], v[54:55], v[58:59] op_sel_hi:[1,0]
	v_pk_fma_f32 v[84:85], v[56:57], v[58:59], v[84:85] op_sel:[0,1,0]
	v_pk_fma_f32 v[84:85], v[66:67], v[60:61], v[84:85] op_sel_hi:[1,0,1]
	v_pk_fma_f32 v[84:85], v[68:69], v[60:61], v[84:85] op_sel:[0,1,0]
	ds_read_b128 v[58:61], v121 offset:27648
	v_add_f32_dpp v88, v149, v148 quad_perm:[1,0,3,2] row_mask:0xf bank_mask:0xf bound_ctrl:1
	s_waitcnt lgkmcnt(5)
	v_pk_mul_f32 v[140:141], v[82:83], v[62:63] op_sel_hi:[1,0]
	v_add_f32_dpp v86, v85, v84 quad_perm:[1,0,3,2] row_mask:0xf bank_mask:0xf bound_ctrl:1
	v_pk_mul_f32 v[142:143], v[82:83], v[62:63] op_sel:[0,1]
	v_add_f32_dpp v88, v88, v88 quad_perm:[2,3,0,1] row_mask:0xf bank_mask:0xf bound_ctrl:1
	v_pk_mul_f32 v[144:145], v[82:83], v[64:65] op_sel_hi:[1,0]
	v_add_f32_dpp v86, v86, v86 quad_perm:[2,3,0,1] row_mask:0xf bank_mask:0xf bound_ctrl:1
	v_pk_mul_f32 v[146:147], v[82:83], v[64:65] op_sel:[0,1]
	ds_read_b128 v[62:65], v121 offset:19456
	ds_read_b32 v82, v123 offset:42496
	ds_read_b32 v83, v89 offset:42496
	v_add_f32_dpp v88, v88, v88 row_ror:4 row_mask:0xf bank_mask:0xf bound_ctrl:1
	s_waitcnt lgkmcnt(7)
	v_pk_fma_f32 v[140:141], v[54:55], v[70:71], v[140:141] op_sel_hi:[1,0,1]
	v_add_f32_dpp v86, v86, v86 row_ror:4 row_mask:0xf bank_mask:0xf bound_ctrl:1
	v_pk_fma_f32 v[142:143], v[56:57], v[70:71], v[142:143] op_sel:[0,1,0]
	v_add_f32_dpp v88, v88, v88 row_ror:8 row_mask:0xf bank_mask:0xf bound_ctrl:1
	v_pk_fma_f32 v[144:145], v[66:67], v[72:73], v[144:145] op_sel_hi:[1,0,1]
	v_add_f32_dpp v86, v86, v86 row_ror:8 row_mask:0xf bank_mask:0xf bound_ctrl:1
	v_pk_fma_f32 v[146:147], v[68:69], v[72:73], v[146:147] op_sel:[0,1,0]
	ds_read_b128 v[70:73], v121 offset:11264
	ds_write_b32 v123, v88 offset:46336
	v_mov_b32_dpp v87, v86 quad_perm:[1,0,3,2] row_mask:0xf bank_mask:0xf bound_ctrl:1
	s_waitcnt lgkmcnt(7)
	v_pk_fma_f32 v[54:55], v[86:87], v[74:75], v[140:141] op_sel_hi:[1,0,1]
	v_pk_fma_f32 v[56:57], v[86:87], v[74:75], v[142:143] op_sel:[0,1,0]
	v_pk_fma_f32 v[66:67], v[86:87], v[76:77], v[144:145] op_sel_hi:[1,0,1]
	v_pk_fma_f32 v[68:69], v[86:87], v[76:77], v[146:147] op_sel:[0,1,0]
	ds_read_b128 v[74:77], v121 offset:35840
	s_waitcnt lgkmcnt(7)
	v_pk_mul_f32 v[148:149], v[54:55], v[78:79] op_sel_hi:[1,0]
	v_pk_fma_f32 v[148:149], v[56:57], v[78:79], v[148:149] op_sel:[0,1,0]
	v_pk_fma_f32 v[148:149], v[66:67], v[80:81], v[148:149] op_sel_hi:[1,0,1]
	v_pk_fma_f32 v[148:149], v[68:69], v[80:81], v[148:149] op_sel:[0,1,0]
	ds_read_b128 v[78:81], v121 offset:3072
	s_waitcnt lgkmcnt(7)
	v_pk_mul_f32 v[84:85], v[54:55], v[58:59] op_sel_hi:[1,0]
	v_pk_fma_f32 v[84:85], v[56:57], v[58:59], v[84:85] op_sel:[0,1,0]
	v_pk_fma_f32 v[84:85], v[66:67], v[60:61], v[84:85] op_sel_hi:[1,0,1]
	v_pk_fma_f32 v[84:85], v[68:69], v[60:61], v[84:85] op_sel:[0,1,0]
	ds_read_b128 v[58:61], v121 offset:27904
	v_add_f32_dpp v88, v149, v148 quad_perm:[1,0,3,2] row_mask:0xf bank_mask:0xf bound_ctrl:1
	s_waitcnt lgkmcnt(5)
	v_pk_mul_f32 v[140:141], v[82:83], v[62:63] op_sel_hi:[1,0]
	v_add_f32_dpp v86, v85, v84 quad_perm:[1,0,3,2] row_mask:0xf bank_mask:0xf bound_ctrl:1
	v_pk_mul_f32 v[142:143], v[82:83], v[62:63] op_sel:[0,1]
	v_add_f32_dpp v88, v88, v88 quad_perm:[2,3,0,1] row_mask:0xf bank_mask:0xf bound_ctrl:1
	v_pk_mul_f32 v[144:145], v[82:83], v[64:65] op_sel_hi:[1,0]
	v_add_f32_dpp v86, v86, v86 quad_perm:[2,3,0,1] row_mask:0xf bank_mask:0xf bound_ctrl:1
	v_pk_mul_f32 v[146:147], v[82:83], v[64:65] op_sel:[0,1]
	ds_read_b128 v[62:65], v121 offset:19712
	ds_read_b32 v82, v123 offset:42624
	ds_read_b32 v83, v89 offset:42624
	v_add_f32_dpp v88, v88, v88 row_ror:4 row_mask:0xf bank_mask:0xf bound_ctrl:1
	s_waitcnt lgkmcnt(7)
	v_pk_fma_f32 v[140:141], v[54:55], v[70:71], v[140:141] op_sel_hi:[1,0,1]
	v_add_f32_dpp v86, v86, v86 row_ror:4 row_mask:0xf bank_mask:0xf bound_ctrl:1
	v_pk_fma_f32 v[142:143], v[56:57], v[70:71], v[142:143] op_sel:[0,1,0]
	v_add_f32_dpp v88, v88, v88 row_ror:8 row_mask:0xf bank_mask:0xf bound_ctrl:1
	v_pk_fma_f32 v[144:145], v[66:67], v[72:73], v[144:145] op_sel_hi:[1,0,1]
	v_add_f32_dpp v86, v86, v86 row_ror:8 row_mask:0xf bank_mask:0xf bound_ctrl:1
	v_pk_fma_f32 v[146:147], v[68:69], v[72:73], v[146:147] op_sel:[0,1,0]
	ds_read_b128 v[70:73], v121 offset:11520
	ds_write_b32 v123, v88 offset:46464
	v_mov_b32_dpp v87, v86 quad_perm:[1,0,3,2] row_mask:0xf bank_mask:0xf bound_ctrl:1
	s_waitcnt lgkmcnt(7)
	v_pk_fma_f32 v[54:55], v[86:87], v[74:75], v[140:141] op_sel_hi:[1,0,1]
	v_pk_fma_f32 v[56:57], v[86:87], v[74:75], v[142:143] op_sel:[0,1,0]
	v_pk_fma_f32 v[66:67], v[86:87], v[76:77], v[144:145] op_sel_hi:[1,0,1]
	v_pk_fma_f32 v[68:69], v[86:87], v[76:77], v[146:147] op_sel:[0,1,0]
	ds_read_b128 v[74:77], v121 offset:36096
	s_waitcnt lgkmcnt(7)
	v_pk_mul_f32 v[148:149], v[54:55], v[78:79] op_sel_hi:[1,0]
	v_pk_fma_f32 v[148:149], v[56:57], v[78:79], v[148:149] op_sel:[0,1,0]
	v_pk_fma_f32 v[148:149], v[66:67], v[80:81], v[148:149] op_sel_hi:[1,0,1]
	v_pk_fma_f32 v[148:149], v[68:69], v[80:81], v[148:149] op_sel:[0,1,0]
	ds_read_b128 v[78:81], v121 offset:3328
	s_waitcnt lgkmcnt(7)
	v_pk_mul_f32 v[84:85], v[54:55], v[58:59] op_sel_hi:[1,0]
	v_pk_fma_f32 v[84:85], v[56:57], v[58:59], v[84:85] op_sel:[0,1,0]
	v_pk_fma_f32 v[84:85], v[66:67], v[60:61], v[84:85] op_sel_hi:[1,0,1]
	v_pk_fma_f32 v[84:85], v[68:69], v[60:61], v[84:85] op_sel:[0,1,0]
	ds_read_b128 v[58:61], v121 offset:28160
	v_add_f32_dpp v88, v149, v148 quad_perm:[1,0,3,2] row_mask:0xf bank_mask:0xf bound_ctrl:1
	s_waitcnt lgkmcnt(5)
	v_pk_mul_f32 v[140:141], v[82:83], v[62:63] op_sel_hi:[1,0]
	v_add_f32_dpp v86, v85, v84 quad_perm:[1,0,3,2] row_mask:0xf bank_mask:0xf bound_ctrl:1
	v_pk_mul_f32 v[142:143], v[82:83], v[62:63] op_sel:[0,1]
	v_add_f32_dpp v88, v88, v88 quad_perm:[2,3,0,1] row_mask:0xf bank_mask:0xf bound_ctrl:1
	v_pk_mul_f32 v[144:145], v[82:83], v[64:65] op_sel_hi:[1,0]
	v_add_f32_dpp v86, v86, v86 quad_perm:[2,3,0,1] row_mask:0xf bank_mask:0xf bound_ctrl:1
	v_pk_mul_f32 v[146:147], v[82:83], v[64:65] op_sel:[0,1]
	ds_read_b128 v[62:65], v121 offset:19968
	ds_read_b32 v82, v123 offset:42752
	ds_read_b32 v83, v89 offset:42752
	v_add_f32_dpp v88, v88, v88 row_ror:4 row_mask:0xf bank_mask:0xf bound_ctrl:1
	s_waitcnt lgkmcnt(7)
	v_pk_fma_f32 v[140:141], v[54:55], v[70:71], v[140:141] op_sel_hi:[1,0,1]
	v_add_f32_dpp v86, v86, v86 row_ror:4 row_mask:0xf bank_mask:0xf bound_ctrl:1
	v_pk_fma_f32 v[142:143], v[56:57], v[70:71], v[142:143] op_sel:[0,1,0]
	v_add_f32_dpp v88, v88, v88 row_ror:8 row_mask:0xf bank_mask:0xf bound_ctrl:1
	v_pk_fma_f32 v[144:145], v[66:67], v[72:73], v[144:145] op_sel_hi:[1,0,1]
	v_add_f32_dpp v86, v86, v86 row_ror:8 row_mask:0xf bank_mask:0xf bound_ctrl:1
	v_pk_fma_f32 v[146:147], v[68:69], v[72:73], v[146:147] op_sel:[0,1,0]
	ds_read_b128 v[70:73], v121 offset:11776
	ds_write_b32 v123, v88 offset:46592
	v_mov_b32_dpp v87, v86 quad_perm:[1,0,3,2] row_mask:0xf bank_mask:0xf bound_ctrl:1
	s_waitcnt lgkmcnt(7)
	v_pk_fma_f32 v[54:55], v[86:87], v[74:75], v[140:141] op_sel_hi:[1,0,1]
	v_pk_fma_f32 v[56:57], v[86:87], v[74:75], v[142:143] op_sel:[0,1,0]
	v_pk_fma_f32 v[66:67], v[86:87], v[76:77], v[144:145] op_sel_hi:[1,0,1]
	v_pk_fma_f32 v[68:69], v[86:87], v[76:77], v[146:147] op_sel:[0,1,0]
	ds_read_b128 v[74:77], v121 offset:36352
	s_waitcnt lgkmcnt(7)
	v_pk_mul_f32 v[148:149], v[54:55], v[78:79] op_sel_hi:[1,0]
	v_pk_fma_f32 v[148:149], v[56:57], v[78:79], v[148:149] op_sel:[0,1,0]
	v_pk_fma_f32 v[148:149], v[66:67], v[80:81], v[148:149] op_sel_hi:[1,0,1]
	v_pk_fma_f32 v[148:149], v[68:69], v[80:81], v[148:149] op_sel:[0,1,0]
	ds_read_b128 v[78:81], v121 offset:3584
	s_waitcnt lgkmcnt(7)
	v_pk_mul_f32 v[84:85], v[54:55], v[58:59] op_sel_hi:[1,0]
	v_pk_fma_f32 v[84:85], v[56:57], v[58:59], v[84:85] op_sel:[0,1,0]
	v_pk_fma_f32 v[84:85], v[66:67], v[60:61], v[84:85] op_sel_hi:[1,0,1]
	v_pk_fma_f32 v[84:85], v[68:69], v[60:61], v[84:85] op_sel:[0,1,0]
	ds_read_b128 v[58:61], v121 offset:28416
	v_add_f32_dpp v88, v149, v148 quad_perm:[1,0,3,2] row_mask:0xf bank_mask:0xf bound_ctrl:1
	s_waitcnt lgkmcnt(5)
	v_pk_mul_f32 v[140:141], v[82:83], v[62:63] op_sel_hi:[1,0]
	v_add_f32_dpp v86, v85, v84 quad_perm:[1,0,3,2] row_mask:0xf bank_mask:0xf bound_ctrl:1
	v_pk_mul_f32 v[142:143], v[82:83], v[62:63] op_sel:[0,1]
	v_add_f32_dpp v88, v88, v88 quad_perm:[2,3,0,1] row_mask:0xf bank_mask:0xf bound_ctrl:1
	v_pk_mul_f32 v[144:145], v[82:83], v[64:65] op_sel_hi:[1,0]
	v_add_f32_dpp v86, v86, v86 quad_perm:[2,3,0,1] row_mask:0xf bank_mask:0xf bound_ctrl:1
	v_pk_mul_f32 v[146:147], v[82:83], v[64:65] op_sel:[0,1]
	ds_read_b128 v[62:65], v121 offset:20224
	ds_read_b32 v82, v123 offset:42880
	ds_read_b32 v83, v89 offset:42880
	v_add_f32_dpp v88, v88, v88 row_ror:4 row_mask:0xf bank_mask:0xf bound_ctrl:1
	s_waitcnt lgkmcnt(7)
	v_pk_fma_f32 v[140:141], v[54:55], v[70:71], v[140:141] op_sel_hi:[1,0,1]
	v_add_f32_dpp v86, v86, v86 row_ror:4 row_mask:0xf bank_mask:0xf bound_ctrl:1
	v_pk_fma_f32 v[142:143], v[56:57], v[70:71], v[142:143] op_sel:[0,1,0]
	v_add_f32_dpp v88, v88, v88 row_ror:8 row_mask:0xf bank_mask:0xf bound_ctrl:1
	v_pk_fma_f32 v[144:145], v[66:67], v[72:73], v[144:145] op_sel_hi:[1,0,1]
	v_add_f32_dpp v86, v86, v86 row_ror:8 row_mask:0xf bank_mask:0xf bound_ctrl:1
	v_pk_fma_f32 v[146:147], v[68:69], v[72:73], v[146:147] op_sel:[0,1,0]
	ds_read_b128 v[70:73], v121 offset:12032
	ds_write_b32 v123, v88 offset:46720
	v_mov_b32_dpp v87, v86 quad_perm:[1,0,3,2] row_mask:0xf bank_mask:0xf bound_ctrl:1
	s_waitcnt lgkmcnt(7)
	v_pk_fma_f32 v[54:55], v[86:87], v[74:75], v[140:141] op_sel_hi:[1,0,1]
	v_pk_fma_f32 v[56:57], v[86:87], v[74:75], v[142:143] op_sel:[0,1,0]
	v_pk_fma_f32 v[66:67], v[86:87], v[76:77], v[144:145] op_sel_hi:[1,0,1]
	v_pk_fma_f32 v[68:69], v[86:87], v[76:77], v[146:147] op_sel:[0,1,0]
	ds_read_b128 v[74:77], v121 offset:36608
	s_waitcnt lgkmcnt(7)
	v_pk_mul_f32 v[148:149], v[54:55], v[78:79] op_sel_hi:[1,0]
	v_pk_fma_f32 v[148:149], v[56:57], v[78:79], v[148:149] op_sel:[0,1,0]
	v_pk_fma_f32 v[148:149], v[66:67], v[80:81], v[148:149] op_sel_hi:[1,0,1]
	v_pk_fma_f32 v[148:149], v[68:69], v[80:81], v[148:149] op_sel:[0,1,0]
	ds_read_b128 v[78:81], v121 offset:3840
	s_waitcnt lgkmcnt(7)
	v_pk_mul_f32 v[84:85], v[54:55], v[58:59] op_sel_hi:[1,0]
	v_pk_fma_f32 v[84:85], v[56:57], v[58:59], v[84:85] op_sel:[0,1,0]
	v_pk_fma_f32 v[84:85], v[66:67], v[60:61], v[84:85] op_sel_hi:[1,0,1]
	v_pk_fma_f32 v[84:85], v[68:69], v[60:61], v[84:85] op_sel:[0,1,0]
	ds_read_b128 v[58:61], v121 offset:28672
	v_add_f32_dpp v88, v149, v148 quad_perm:[1,0,3,2] row_mask:0xf bank_mask:0xf bound_ctrl:1
	s_waitcnt lgkmcnt(5)
	v_pk_mul_f32 v[140:141], v[82:83], v[62:63] op_sel_hi:[1,0]
	v_add_f32_dpp v86, v85, v84 quad_perm:[1,0,3,2] row_mask:0xf bank_mask:0xf bound_ctrl:1
	v_pk_mul_f32 v[142:143], v[82:83], v[62:63] op_sel:[0,1]
	v_add_f32_dpp v88, v88, v88 quad_perm:[2,3,0,1] row_mask:0xf bank_mask:0xf bound_ctrl:1
	v_pk_mul_f32 v[144:145], v[82:83], v[64:65] op_sel_hi:[1,0]
	v_add_f32_dpp v86, v86, v86 quad_perm:[2,3,0,1] row_mask:0xf bank_mask:0xf bound_ctrl:1
	v_pk_mul_f32 v[146:147], v[82:83], v[64:65] op_sel:[0,1]
	ds_read_b128 v[62:65], v121 offset:20480
	ds_read_b32 v82, v123 offset:43008
	ds_read_b32 v83, v89 offset:43008
	v_add_f32_dpp v88, v88, v88 row_ror:4 row_mask:0xf bank_mask:0xf bound_ctrl:1
	s_waitcnt lgkmcnt(7)
	v_pk_fma_f32 v[140:141], v[54:55], v[70:71], v[140:141] op_sel_hi:[1,0,1]
	v_add_f32_dpp v86, v86, v86 row_ror:4 row_mask:0xf bank_mask:0xf bound_ctrl:1
	v_pk_fma_f32 v[142:143], v[56:57], v[70:71], v[142:143] op_sel:[0,1,0]
	v_add_f32_dpp v88, v88, v88 row_ror:8 row_mask:0xf bank_mask:0xf bound_ctrl:1
	v_pk_fma_f32 v[144:145], v[66:67], v[72:73], v[144:145] op_sel_hi:[1,0,1]
	v_add_f32_dpp v86, v86, v86 row_ror:8 row_mask:0xf bank_mask:0xf bound_ctrl:1
	v_pk_fma_f32 v[146:147], v[68:69], v[72:73], v[146:147] op_sel:[0,1,0]
	ds_read_b128 v[70:73], v121 offset:12288
	ds_write_b32 v123, v88 offset:46848
	v_mov_b32_dpp v87, v86 quad_perm:[1,0,3,2] row_mask:0xf bank_mask:0xf bound_ctrl:1
	s_waitcnt lgkmcnt(7)
	v_pk_fma_f32 v[54:55], v[86:87], v[74:75], v[140:141] op_sel_hi:[1,0,1]
	v_pk_fma_f32 v[56:57], v[86:87], v[74:75], v[142:143] op_sel:[0,1,0]
	v_pk_fma_f32 v[66:67], v[86:87], v[76:77], v[144:145] op_sel_hi:[1,0,1]
	v_pk_fma_f32 v[68:69], v[86:87], v[76:77], v[146:147] op_sel:[0,1,0]
	ds_read_b128 v[74:77], v121 offset:36864
	s_waitcnt lgkmcnt(7)
	v_pk_mul_f32 v[148:149], v[54:55], v[78:79] op_sel_hi:[1,0]
	v_pk_fma_f32 v[148:149], v[56:57], v[78:79], v[148:149] op_sel:[0,1,0]
	v_pk_fma_f32 v[148:149], v[66:67], v[80:81], v[148:149] op_sel_hi:[1,0,1]
	v_pk_fma_f32 v[148:149], v[68:69], v[80:81], v[148:149] op_sel:[0,1,0]
	ds_read_b128 v[78:81], v121 offset:4096
	s_waitcnt lgkmcnt(7)
	v_pk_mul_f32 v[84:85], v[54:55], v[58:59] op_sel_hi:[1,0]
	v_pk_fma_f32 v[84:85], v[56:57], v[58:59], v[84:85] op_sel:[0,1,0]
	v_pk_fma_f32 v[84:85], v[66:67], v[60:61], v[84:85] op_sel_hi:[1,0,1]
	v_pk_fma_f32 v[84:85], v[68:69], v[60:61], v[84:85] op_sel:[0,1,0]
	ds_read_b128 v[58:61], v121 offset:28928
	v_add_f32_dpp v88, v149, v148 quad_perm:[1,0,3,2] row_mask:0xf bank_mask:0xf bound_ctrl:1
	s_waitcnt lgkmcnt(5)
	v_pk_mul_f32 v[140:141], v[82:83], v[62:63] op_sel_hi:[1,0]
	v_add_f32_dpp v86, v85, v84 quad_perm:[1,0,3,2] row_mask:0xf bank_mask:0xf bound_ctrl:1
	v_pk_mul_f32 v[142:143], v[82:83], v[62:63] op_sel:[0,1]
	v_add_f32_dpp v88, v88, v88 quad_perm:[2,3,0,1] row_mask:0xf bank_mask:0xf bound_ctrl:1
	v_pk_mul_f32 v[144:145], v[82:83], v[64:65] op_sel_hi:[1,0]
	v_add_f32_dpp v86, v86, v86 quad_perm:[2,3,0,1] row_mask:0xf bank_mask:0xf bound_ctrl:1
	v_pk_mul_f32 v[146:147], v[82:83], v[64:65] op_sel:[0,1]
	ds_read_b128 v[62:65], v121 offset:20736
	ds_read_b32 v82, v123 offset:43136
	ds_read_b32 v83, v89 offset:43136
	v_add_f32_dpp v88, v88, v88 row_ror:4 row_mask:0xf bank_mask:0xf bound_ctrl:1
	s_waitcnt lgkmcnt(7)
	v_pk_fma_f32 v[140:141], v[54:55], v[70:71], v[140:141] op_sel_hi:[1,0,1]
	v_add_f32_dpp v86, v86, v86 row_ror:4 row_mask:0xf bank_mask:0xf bound_ctrl:1
	v_pk_fma_f32 v[142:143], v[56:57], v[70:71], v[142:143] op_sel:[0,1,0]
	v_add_f32_dpp v88, v88, v88 row_ror:8 row_mask:0xf bank_mask:0xf bound_ctrl:1
	v_pk_fma_f32 v[144:145], v[66:67], v[72:73], v[144:145] op_sel_hi:[1,0,1]
	v_add_f32_dpp v86, v86, v86 row_ror:8 row_mask:0xf bank_mask:0xf bound_ctrl:1
	v_pk_fma_f32 v[146:147], v[68:69], v[72:73], v[146:147] op_sel:[0,1,0]
	ds_read_b128 v[70:73], v121 offset:12544
	ds_write_b32 v123, v88 offset:46976
	v_mov_b32_dpp v87, v86 quad_perm:[1,0,3,2] row_mask:0xf bank_mask:0xf bound_ctrl:1
	s_waitcnt lgkmcnt(7)
	v_pk_fma_f32 v[54:55], v[86:87], v[74:75], v[140:141] op_sel_hi:[1,0,1]
	v_pk_fma_f32 v[56:57], v[86:87], v[74:75], v[142:143] op_sel:[0,1,0]
	v_pk_fma_f32 v[66:67], v[86:87], v[76:77], v[144:145] op_sel_hi:[1,0,1]
	v_pk_fma_f32 v[68:69], v[86:87], v[76:77], v[146:147] op_sel:[0,1,0]
	ds_read_b128 v[74:77], v121 offset:37120
	s_waitcnt lgkmcnt(7)
	v_pk_mul_f32 v[148:149], v[54:55], v[78:79] op_sel_hi:[1,0]
	v_pk_fma_f32 v[148:149], v[56:57], v[78:79], v[148:149] op_sel:[0,1,0]
	v_pk_fma_f32 v[148:149], v[66:67], v[80:81], v[148:149] op_sel_hi:[1,0,1]
	v_pk_fma_f32 v[148:149], v[68:69], v[80:81], v[148:149] op_sel:[0,1,0]
	ds_read_b128 v[78:81], v121 offset:4352
	s_waitcnt lgkmcnt(7)
	v_pk_mul_f32 v[84:85], v[54:55], v[58:59] op_sel_hi:[1,0]
	v_pk_fma_f32 v[84:85], v[56:57], v[58:59], v[84:85] op_sel:[0,1,0]
	v_pk_fma_f32 v[84:85], v[66:67], v[60:61], v[84:85] op_sel_hi:[1,0,1]
	v_pk_fma_f32 v[84:85], v[68:69], v[60:61], v[84:85] op_sel:[0,1,0]
	ds_read_b128 v[58:61], v121 offset:29184
	v_add_f32_dpp v88, v149, v148 quad_perm:[1,0,3,2] row_mask:0xf bank_mask:0xf bound_ctrl:1
	s_waitcnt lgkmcnt(5)
	v_pk_mul_f32 v[140:141], v[82:83], v[62:63] op_sel_hi:[1,0]
	v_add_f32_dpp v86, v85, v84 quad_perm:[1,0,3,2] row_mask:0xf bank_mask:0xf bound_ctrl:1
	v_pk_mul_f32 v[142:143], v[82:83], v[62:63] op_sel:[0,1]
	v_add_f32_dpp v88, v88, v88 quad_perm:[2,3,0,1] row_mask:0xf bank_mask:0xf bound_ctrl:1
	v_pk_mul_f32 v[144:145], v[82:83], v[64:65] op_sel_hi:[1,0]
	v_add_f32_dpp v86, v86, v86 quad_perm:[2,3,0,1] row_mask:0xf bank_mask:0xf bound_ctrl:1
	v_pk_mul_f32 v[146:147], v[82:83], v[64:65] op_sel:[0,1]
	ds_read_b128 v[62:65], v121 offset:20992
	ds_read_b32 v82, v123 offset:43264
	ds_read_b32 v83, v89 offset:43264
	v_add_f32_dpp v88, v88, v88 row_ror:4 row_mask:0xf bank_mask:0xf bound_ctrl:1
	s_waitcnt lgkmcnt(7)
	v_pk_fma_f32 v[140:141], v[54:55], v[70:71], v[140:141] op_sel_hi:[1,0,1]
	v_add_f32_dpp v86, v86, v86 row_ror:4 row_mask:0xf bank_mask:0xf bound_ctrl:1
	v_pk_fma_f32 v[142:143], v[56:57], v[70:71], v[142:143] op_sel:[0,1,0]
	v_add_f32_dpp v88, v88, v88 row_ror:8 row_mask:0xf bank_mask:0xf bound_ctrl:1
	v_pk_fma_f32 v[144:145], v[66:67], v[72:73], v[144:145] op_sel_hi:[1,0,1]
	v_add_f32_dpp v86, v86, v86 row_ror:8 row_mask:0xf bank_mask:0xf bound_ctrl:1
	v_pk_fma_f32 v[146:147], v[68:69], v[72:73], v[146:147] op_sel:[0,1,0]
	ds_read_b128 v[70:73], v121 offset:12800
	ds_write_b32 v123, v88 offset:47104
	v_mov_b32_dpp v87, v86 quad_perm:[1,0,3,2] row_mask:0xf bank_mask:0xf bound_ctrl:1
	s_waitcnt lgkmcnt(7)
	v_pk_fma_f32 v[54:55], v[86:87], v[74:75], v[140:141] op_sel_hi:[1,0,1]
	v_pk_fma_f32 v[56:57], v[86:87], v[74:75], v[142:143] op_sel:[0,1,0]
	v_pk_fma_f32 v[66:67], v[86:87], v[76:77], v[144:145] op_sel_hi:[1,0,1]
	v_pk_fma_f32 v[68:69], v[86:87], v[76:77], v[146:147] op_sel:[0,1,0]
	ds_read_b128 v[74:77], v121 offset:37376
	s_waitcnt lgkmcnt(7)
	v_pk_mul_f32 v[148:149], v[54:55], v[78:79] op_sel_hi:[1,0]
	v_pk_fma_f32 v[148:149], v[56:57], v[78:79], v[148:149] op_sel:[0,1,0]
	v_pk_fma_f32 v[148:149], v[66:67], v[80:81], v[148:149] op_sel_hi:[1,0,1]
	v_pk_fma_f32 v[148:149], v[68:69], v[80:81], v[148:149] op_sel:[0,1,0]
	ds_read_b128 v[78:81], v121 offset:4608
	s_waitcnt lgkmcnt(7)
	v_pk_mul_f32 v[84:85], v[54:55], v[58:59] op_sel_hi:[1,0]
	v_pk_fma_f32 v[84:85], v[56:57], v[58:59], v[84:85] op_sel:[0,1,0]
	v_pk_fma_f32 v[84:85], v[66:67], v[60:61], v[84:85] op_sel_hi:[1,0,1]
	v_pk_fma_f32 v[84:85], v[68:69], v[60:61], v[84:85] op_sel:[0,1,0]
	ds_read_b128 v[58:61], v121 offset:29440
	v_add_f32_dpp v88, v149, v148 quad_perm:[1,0,3,2] row_mask:0xf bank_mask:0xf bound_ctrl:1
	s_waitcnt lgkmcnt(5)
	v_pk_mul_f32 v[140:141], v[82:83], v[62:63] op_sel_hi:[1,0]
	v_add_f32_dpp v86, v85, v84 quad_perm:[1,0,3,2] row_mask:0xf bank_mask:0xf bound_ctrl:1
	v_pk_mul_f32 v[142:143], v[82:83], v[62:63] op_sel:[0,1]
	v_add_f32_dpp v88, v88, v88 quad_perm:[2,3,0,1] row_mask:0xf bank_mask:0xf bound_ctrl:1
	v_pk_mul_f32 v[144:145], v[82:83], v[64:65] op_sel_hi:[1,0]
	v_add_f32_dpp v86, v86, v86 quad_perm:[2,3,0,1] row_mask:0xf bank_mask:0xf bound_ctrl:1
	v_pk_mul_f32 v[146:147], v[82:83], v[64:65] op_sel:[0,1]
	ds_read_b128 v[62:65], v121 offset:21248
	ds_read_b32 v82, v123 offset:43392
	ds_read_b32 v83, v89 offset:43392
	v_add_f32_dpp v88, v88, v88 row_ror:4 row_mask:0xf bank_mask:0xf bound_ctrl:1
	s_waitcnt lgkmcnt(7)
	v_pk_fma_f32 v[140:141], v[54:55], v[70:71], v[140:141] op_sel_hi:[1,0,1]
	v_add_f32_dpp v86, v86, v86 row_ror:4 row_mask:0xf bank_mask:0xf bound_ctrl:1
	v_pk_fma_f32 v[142:143], v[56:57], v[70:71], v[142:143] op_sel:[0,1,0]
	v_add_f32_dpp v88, v88, v88 row_ror:8 row_mask:0xf bank_mask:0xf bound_ctrl:1
	v_pk_fma_f32 v[144:145], v[66:67], v[72:73], v[144:145] op_sel_hi:[1,0,1]
	v_add_f32_dpp v86, v86, v86 row_ror:8 row_mask:0xf bank_mask:0xf bound_ctrl:1
	v_pk_fma_f32 v[146:147], v[68:69], v[72:73], v[146:147] op_sel:[0,1,0]
	ds_read_b128 v[70:73], v121 offset:13056
	ds_write_b32 v123, v88 offset:47232
	v_mov_b32_dpp v87, v86 quad_perm:[1,0,3,2] row_mask:0xf bank_mask:0xf bound_ctrl:1
	s_waitcnt lgkmcnt(7)
	v_pk_fma_f32 v[54:55], v[86:87], v[74:75], v[140:141] op_sel_hi:[1,0,1]
	v_pk_fma_f32 v[56:57], v[86:87], v[74:75], v[142:143] op_sel:[0,1,0]
	v_pk_fma_f32 v[66:67], v[86:87], v[76:77], v[144:145] op_sel_hi:[1,0,1]
	v_pk_fma_f32 v[68:69], v[86:87], v[76:77], v[146:147] op_sel:[0,1,0]
	ds_read_b128 v[74:77], v121 offset:37632
	s_waitcnt lgkmcnt(7)
	v_pk_mul_f32 v[148:149], v[54:55], v[78:79] op_sel_hi:[1,0]
	v_pk_fma_f32 v[148:149], v[56:57], v[78:79], v[148:149] op_sel:[0,1,0]
	v_pk_fma_f32 v[148:149], v[66:67], v[80:81], v[148:149] op_sel_hi:[1,0,1]
	v_pk_fma_f32 v[148:149], v[68:69], v[80:81], v[148:149] op_sel:[0,1,0]
	ds_read_b128 v[78:81], v121 offset:4864
	s_waitcnt lgkmcnt(7)
	v_pk_mul_f32 v[84:85], v[54:55], v[58:59] op_sel_hi:[1,0]
	v_pk_fma_f32 v[84:85], v[56:57], v[58:59], v[84:85] op_sel:[0,1,0]
	v_pk_fma_f32 v[84:85], v[66:67], v[60:61], v[84:85] op_sel_hi:[1,0,1]
	v_pk_fma_f32 v[84:85], v[68:69], v[60:61], v[84:85] op_sel:[0,1,0]
	ds_read_b128 v[58:61], v121 offset:29696
	v_add_f32_dpp v88, v149, v148 quad_perm:[1,0,3,2] row_mask:0xf bank_mask:0xf bound_ctrl:1
	s_waitcnt lgkmcnt(5)
	v_pk_mul_f32 v[140:141], v[82:83], v[62:63] op_sel_hi:[1,0]
	v_add_f32_dpp v86, v85, v84 quad_perm:[1,0,3,2] row_mask:0xf bank_mask:0xf bound_ctrl:1
	v_pk_mul_f32 v[142:143], v[82:83], v[62:63] op_sel:[0,1]
	v_add_f32_dpp v88, v88, v88 quad_perm:[2,3,0,1] row_mask:0xf bank_mask:0xf bound_ctrl:1
	v_pk_mul_f32 v[144:145], v[82:83], v[64:65] op_sel_hi:[1,0]
	v_add_f32_dpp v86, v86, v86 quad_perm:[2,3,0,1] row_mask:0xf bank_mask:0xf bound_ctrl:1
	v_pk_mul_f32 v[146:147], v[82:83], v[64:65] op_sel:[0,1]
	ds_read_b128 v[62:65], v121 offset:21504
	ds_read_b32 v82, v123 offset:43520
	ds_read_b32 v83, v89 offset:43520
	v_add_f32_dpp v88, v88, v88 row_ror:4 row_mask:0xf bank_mask:0xf bound_ctrl:1
	s_waitcnt lgkmcnt(7)
	v_pk_fma_f32 v[140:141], v[54:55], v[70:71], v[140:141] op_sel_hi:[1,0,1]
	v_add_f32_dpp v86, v86, v86 row_ror:4 row_mask:0xf bank_mask:0xf bound_ctrl:1
	v_pk_fma_f32 v[142:143], v[56:57], v[70:71], v[142:143] op_sel:[0,1,0]
	v_add_f32_dpp v88, v88, v88 row_ror:8 row_mask:0xf bank_mask:0xf bound_ctrl:1
	v_pk_fma_f32 v[144:145], v[66:67], v[72:73], v[144:145] op_sel_hi:[1,0,1]
	v_add_f32_dpp v86, v86, v86 row_ror:8 row_mask:0xf bank_mask:0xf bound_ctrl:1
	v_pk_fma_f32 v[146:147], v[68:69], v[72:73], v[146:147] op_sel:[0,1,0]
	ds_read_b128 v[70:73], v121 offset:13312
	ds_write_b32 v123, v88 offset:47360
	v_mov_b32_dpp v87, v86 quad_perm:[1,0,3,2] row_mask:0xf bank_mask:0xf bound_ctrl:1
	s_waitcnt lgkmcnt(7)
	v_pk_fma_f32 v[54:55], v[86:87], v[74:75], v[140:141] op_sel_hi:[1,0,1]
	v_pk_fma_f32 v[56:57], v[86:87], v[74:75], v[142:143] op_sel:[0,1,0]
	v_pk_fma_f32 v[66:67], v[86:87], v[76:77], v[144:145] op_sel_hi:[1,0,1]
	v_pk_fma_f32 v[68:69], v[86:87], v[76:77], v[146:147] op_sel:[0,1,0]
	ds_read_b128 v[74:77], v121 offset:37888
	s_waitcnt lgkmcnt(7)
	v_pk_mul_f32 v[148:149], v[54:55], v[78:79] op_sel_hi:[1,0]
	v_pk_fma_f32 v[148:149], v[56:57], v[78:79], v[148:149] op_sel:[0,1,0]
	v_pk_fma_f32 v[148:149], v[66:67], v[80:81], v[148:149] op_sel_hi:[1,0,1]
	v_pk_fma_f32 v[148:149], v[68:69], v[80:81], v[148:149] op_sel:[0,1,0]
	ds_read_b128 v[78:81], v121 offset:5120
	s_waitcnt lgkmcnt(7)
	v_pk_mul_f32 v[84:85], v[54:55], v[58:59] op_sel_hi:[1,0]
	v_pk_fma_f32 v[84:85], v[56:57], v[58:59], v[84:85] op_sel:[0,1,0]
	v_pk_fma_f32 v[84:85], v[66:67], v[60:61], v[84:85] op_sel_hi:[1,0,1]
	v_pk_fma_f32 v[84:85], v[68:69], v[60:61], v[84:85] op_sel:[0,1,0]
	ds_read_b128 v[58:61], v121 offset:29952
	v_add_f32_dpp v88, v149, v148 quad_perm:[1,0,3,2] row_mask:0xf bank_mask:0xf bound_ctrl:1
	s_waitcnt lgkmcnt(5)
	v_pk_mul_f32 v[140:141], v[82:83], v[62:63] op_sel_hi:[1,0]
	v_add_f32_dpp v86, v85, v84 quad_perm:[1,0,3,2] row_mask:0xf bank_mask:0xf bound_ctrl:1
	v_pk_mul_f32 v[142:143], v[82:83], v[62:63] op_sel:[0,1]
	v_add_f32_dpp v88, v88, v88 quad_perm:[2,3,0,1] row_mask:0xf bank_mask:0xf bound_ctrl:1
	v_pk_mul_f32 v[144:145], v[82:83], v[64:65] op_sel_hi:[1,0]
	v_add_f32_dpp v86, v86, v86 quad_perm:[2,3,0,1] row_mask:0xf bank_mask:0xf bound_ctrl:1
	v_pk_mul_f32 v[146:147], v[82:83], v[64:65] op_sel:[0,1]
	ds_read_b128 v[62:65], v121 offset:21760
	ds_read_b32 v82, v123 offset:43648
	ds_read_b32 v83, v89 offset:43648
	v_add_f32_dpp v88, v88, v88 row_ror:4 row_mask:0xf bank_mask:0xf bound_ctrl:1
	s_waitcnt lgkmcnt(7)
	v_pk_fma_f32 v[140:141], v[54:55], v[70:71], v[140:141] op_sel_hi:[1,0,1]
	v_add_f32_dpp v86, v86, v86 row_ror:4 row_mask:0xf bank_mask:0xf bound_ctrl:1
	v_pk_fma_f32 v[142:143], v[56:57], v[70:71], v[142:143] op_sel:[0,1,0]
	v_add_f32_dpp v88, v88, v88 row_ror:8 row_mask:0xf bank_mask:0xf bound_ctrl:1
	v_pk_fma_f32 v[144:145], v[66:67], v[72:73], v[144:145] op_sel_hi:[1,0,1]
	v_add_f32_dpp v86, v86, v86 row_ror:8 row_mask:0xf bank_mask:0xf bound_ctrl:1
	v_pk_fma_f32 v[146:147], v[68:69], v[72:73], v[146:147] op_sel:[0,1,0]
	ds_read_b128 v[70:73], v121 offset:13568
	ds_write_b32 v123, v88 offset:47488
	v_mov_b32_dpp v87, v86 quad_perm:[1,0,3,2] row_mask:0xf bank_mask:0xf bound_ctrl:1
	s_waitcnt lgkmcnt(7)
	v_pk_fma_f32 v[54:55], v[86:87], v[74:75], v[140:141] op_sel_hi:[1,0,1]
	v_pk_fma_f32 v[56:57], v[86:87], v[74:75], v[142:143] op_sel:[0,1,0]
	v_pk_fma_f32 v[66:67], v[86:87], v[76:77], v[144:145] op_sel_hi:[1,0,1]
	v_pk_fma_f32 v[68:69], v[86:87], v[76:77], v[146:147] op_sel:[0,1,0]
	ds_read_b128 v[74:77], v121 offset:38144
	s_waitcnt lgkmcnt(7)
	v_pk_mul_f32 v[148:149], v[54:55], v[78:79] op_sel_hi:[1,0]
	v_pk_fma_f32 v[148:149], v[56:57], v[78:79], v[148:149] op_sel:[0,1,0]
	v_pk_fma_f32 v[148:149], v[66:67], v[80:81], v[148:149] op_sel_hi:[1,0,1]
	v_pk_fma_f32 v[148:149], v[68:69], v[80:81], v[148:149] op_sel:[0,1,0]
	ds_read_b128 v[78:81], v121 offset:5376
	s_waitcnt lgkmcnt(7)
	v_pk_mul_f32 v[84:85], v[54:55], v[58:59] op_sel_hi:[1,0]
	v_pk_fma_f32 v[84:85], v[56:57], v[58:59], v[84:85] op_sel:[0,1,0]
	v_pk_fma_f32 v[84:85], v[66:67], v[60:61], v[84:85] op_sel_hi:[1,0,1]
	v_pk_fma_f32 v[84:85], v[68:69], v[60:61], v[84:85] op_sel:[0,1,0]
	ds_read_b128 v[58:61], v121 offset:30208
	v_add_f32_dpp v88, v149, v148 quad_perm:[1,0,3,2] row_mask:0xf bank_mask:0xf bound_ctrl:1
	s_waitcnt lgkmcnt(5)
	v_pk_mul_f32 v[140:141], v[82:83], v[62:63] op_sel_hi:[1,0]
	v_add_f32_dpp v86, v85, v84 quad_perm:[1,0,3,2] row_mask:0xf bank_mask:0xf bound_ctrl:1
	v_pk_mul_f32 v[142:143], v[82:83], v[62:63] op_sel:[0,1]
	v_add_f32_dpp v88, v88, v88 quad_perm:[2,3,0,1] row_mask:0xf bank_mask:0xf bound_ctrl:1
	v_pk_mul_f32 v[144:145], v[82:83], v[64:65] op_sel_hi:[1,0]
	v_add_f32_dpp v86, v86, v86 quad_perm:[2,3,0,1] row_mask:0xf bank_mask:0xf bound_ctrl:1
	v_pk_mul_f32 v[146:147], v[82:83], v[64:65] op_sel:[0,1]
	ds_read_b128 v[62:65], v121 offset:22016
	ds_read_b32 v82, v123 offset:43776
	ds_read_b32 v83, v89 offset:43776
	v_add_f32_dpp v88, v88, v88 row_ror:4 row_mask:0xf bank_mask:0xf bound_ctrl:1
	s_waitcnt lgkmcnt(7)
	v_pk_fma_f32 v[140:141], v[54:55], v[70:71], v[140:141] op_sel_hi:[1,0,1]
	v_add_f32_dpp v86, v86, v86 row_ror:4 row_mask:0xf bank_mask:0xf bound_ctrl:1
	v_pk_fma_f32 v[142:143], v[56:57], v[70:71], v[142:143] op_sel:[0,1,0]
	v_add_f32_dpp v88, v88, v88 row_ror:8 row_mask:0xf bank_mask:0xf bound_ctrl:1
	v_pk_fma_f32 v[144:145], v[66:67], v[72:73], v[144:145] op_sel_hi:[1,0,1]
	v_add_f32_dpp v86, v86, v86 row_ror:8 row_mask:0xf bank_mask:0xf bound_ctrl:1
	v_pk_fma_f32 v[146:147], v[68:69], v[72:73], v[146:147] op_sel:[0,1,0]
	ds_read_b128 v[70:73], v121 offset:13824
	ds_write_b32 v123, v88 offset:47616
	v_mov_b32_dpp v87, v86 quad_perm:[1,0,3,2] row_mask:0xf bank_mask:0xf bound_ctrl:1
	s_waitcnt lgkmcnt(7)
	v_pk_fma_f32 v[54:55], v[86:87], v[74:75], v[140:141] op_sel_hi:[1,0,1]
	v_pk_fma_f32 v[56:57], v[86:87], v[74:75], v[142:143] op_sel:[0,1,0]
	v_pk_fma_f32 v[66:67], v[86:87], v[76:77], v[144:145] op_sel_hi:[1,0,1]
	v_pk_fma_f32 v[68:69], v[86:87], v[76:77], v[146:147] op_sel:[0,1,0]
	ds_read_b128 v[74:77], v121 offset:38400
	s_waitcnt lgkmcnt(7)
	v_pk_mul_f32 v[148:149], v[54:55], v[78:79] op_sel_hi:[1,0]
	v_pk_fma_f32 v[148:149], v[56:57], v[78:79], v[148:149] op_sel:[0,1,0]
	v_pk_fma_f32 v[148:149], v[66:67], v[80:81], v[148:149] op_sel_hi:[1,0,1]
	v_pk_fma_f32 v[148:149], v[68:69], v[80:81], v[148:149] op_sel:[0,1,0]
	ds_read_b128 v[78:81], v121 offset:5632
	s_waitcnt lgkmcnt(7)
	v_pk_mul_f32 v[84:85], v[54:55], v[58:59] op_sel_hi:[1,0]
	v_pk_fma_f32 v[84:85], v[56:57], v[58:59], v[84:85] op_sel:[0,1,0]
	v_pk_fma_f32 v[84:85], v[66:67], v[60:61], v[84:85] op_sel_hi:[1,0,1]
	v_pk_fma_f32 v[84:85], v[68:69], v[60:61], v[84:85] op_sel:[0,1,0]
	ds_read_b128 v[58:61], v121 offset:30464
	v_add_f32_dpp v88, v149, v148 quad_perm:[1,0,3,2] row_mask:0xf bank_mask:0xf bound_ctrl:1
	s_waitcnt lgkmcnt(5)
	v_pk_mul_f32 v[140:141], v[82:83], v[62:63] op_sel_hi:[1,0]
	v_add_f32_dpp v86, v85, v84 quad_perm:[1,0,3,2] row_mask:0xf bank_mask:0xf bound_ctrl:1
	v_pk_mul_f32 v[142:143], v[82:83], v[62:63] op_sel:[0,1]
	v_add_f32_dpp v88, v88, v88 quad_perm:[2,3,0,1] row_mask:0xf bank_mask:0xf bound_ctrl:1
	v_pk_mul_f32 v[144:145], v[82:83], v[64:65] op_sel_hi:[1,0]
	v_add_f32_dpp v86, v86, v86 quad_perm:[2,3,0,1] row_mask:0xf bank_mask:0xf bound_ctrl:1
	v_pk_mul_f32 v[146:147], v[82:83], v[64:65] op_sel:[0,1]
	ds_read_b128 v[62:65], v121 offset:22272
	ds_read_b32 v82, v123 offset:43904
	ds_read_b32 v83, v89 offset:43904
	v_add_f32_dpp v88, v88, v88 row_ror:4 row_mask:0xf bank_mask:0xf bound_ctrl:1
	s_waitcnt lgkmcnt(7)
	v_pk_fma_f32 v[140:141], v[54:55], v[70:71], v[140:141] op_sel_hi:[1,0,1]
	v_add_f32_dpp v86, v86, v86 row_ror:4 row_mask:0xf bank_mask:0xf bound_ctrl:1
	v_pk_fma_f32 v[142:143], v[56:57], v[70:71], v[142:143] op_sel:[0,1,0]
	v_add_f32_dpp v88, v88, v88 row_ror:8 row_mask:0xf bank_mask:0xf bound_ctrl:1
	v_pk_fma_f32 v[144:145], v[66:67], v[72:73], v[144:145] op_sel_hi:[1,0,1]
	v_add_f32_dpp v86, v86, v86 row_ror:8 row_mask:0xf bank_mask:0xf bound_ctrl:1
	v_pk_fma_f32 v[146:147], v[68:69], v[72:73], v[146:147] op_sel:[0,1,0]
	ds_read_b128 v[70:73], v121 offset:14080
	ds_write_b32 v123, v88 offset:47744
	v_mov_b32_dpp v87, v86 quad_perm:[1,0,3,2] row_mask:0xf bank_mask:0xf bound_ctrl:1
	s_waitcnt lgkmcnt(7)
	v_pk_fma_f32 v[54:55], v[86:87], v[74:75], v[140:141] op_sel_hi:[1,0,1]
	v_pk_fma_f32 v[56:57], v[86:87], v[74:75], v[142:143] op_sel:[0,1,0]
	v_pk_fma_f32 v[66:67], v[86:87], v[76:77], v[144:145] op_sel_hi:[1,0,1]
	v_pk_fma_f32 v[68:69], v[86:87], v[76:77], v[146:147] op_sel:[0,1,0]
	ds_read_b128 v[74:77], v121 offset:38656
	s_waitcnt lgkmcnt(7)
	v_pk_mul_f32 v[148:149], v[54:55], v[78:79] op_sel_hi:[1,0]
	v_pk_fma_f32 v[148:149], v[56:57], v[78:79], v[148:149] op_sel:[0,1,0]
	v_pk_fma_f32 v[148:149], v[66:67], v[80:81], v[148:149] op_sel_hi:[1,0,1]
	v_pk_fma_f32 v[148:149], v[68:69], v[80:81], v[148:149] op_sel:[0,1,0]
	ds_read_b128 v[78:81], v121 offset:5888
	s_waitcnt lgkmcnt(7)
	v_pk_mul_f32 v[84:85], v[54:55], v[58:59] op_sel_hi:[1,0]
	v_pk_fma_f32 v[84:85], v[56:57], v[58:59], v[84:85] op_sel:[0,1,0]
	v_pk_fma_f32 v[84:85], v[66:67], v[60:61], v[84:85] op_sel_hi:[1,0,1]
	v_pk_fma_f32 v[84:85], v[68:69], v[60:61], v[84:85] op_sel:[0,1,0]
	ds_read_b128 v[58:61], v121 offset:30720
	v_add_f32_dpp v88, v149, v148 quad_perm:[1,0,3,2] row_mask:0xf bank_mask:0xf bound_ctrl:1
	s_waitcnt lgkmcnt(5)
	v_pk_mul_f32 v[140:141], v[82:83], v[62:63] op_sel_hi:[1,0]
	v_add_f32_dpp v86, v85, v84 quad_perm:[1,0,3,2] row_mask:0xf bank_mask:0xf bound_ctrl:1
	v_pk_mul_f32 v[142:143], v[82:83], v[62:63] op_sel:[0,1]
	v_add_f32_dpp v88, v88, v88 quad_perm:[2,3,0,1] row_mask:0xf bank_mask:0xf bound_ctrl:1
	v_pk_mul_f32 v[144:145], v[82:83], v[64:65] op_sel_hi:[1,0]
	v_add_f32_dpp v86, v86, v86 quad_perm:[2,3,0,1] row_mask:0xf bank_mask:0xf bound_ctrl:1
	v_pk_mul_f32 v[146:147], v[82:83], v[64:65] op_sel:[0,1]
	ds_read_b128 v[62:65], v121 offset:22528
	ds_read_b32 v82, v123 offset:44032
	ds_read_b32 v83, v89 offset:44032
	v_add_f32_dpp v88, v88, v88 row_ror:4 row_mask:0xf bank_mask:0xf bound_ctrl:1
	s_waitcnt lgkmcnt(7)
	v_pk_fma_f32 v[140:141], v[54:55], v[70:71], v[140:141] op_sel_hi:[1,0,1]
	v_add_f32_dpp v86, v86, v86 row_ror:4 row_mask:0xf bank_mask:0xf bound_ctrl:1
	v_pk_fma_f32 v[142:143], v[56:57], v[70:71], v[142:143] op_sel:[0,1,0]
	v_add_f32_dpp v88, v88, v88 row_ror:8 row_mask:0xf bank_mask:0xf bound_ctrl:1
	v_pk_fma_f32 v[144:145], v[66:67], v[72:73], v[144:145] op_sel_hi:[1,0,1]
	v_add_f32_dpp v86, v86, v86 row_ror:8 row_mask:0xf bank_mask:0xf bound_ctrl:1
	v_pk_fma_f32 v[146:147], v[68:69], v[72:73], v[146:147] op_sel:[0,1,0]
	ds_read_b128 v[70:73], v121 offset:14336
	ds_write_b32 v123, v88 offset:47872
	v_mov_b32_dpp v87, v86 quad_perm:[1,0,3,2] row_mask:0xf bank_mask:0xf bound_ctrl:1
	s_waitcnt lgkmcnt(7)
	v_pk_fma_f32 v[54:55], v[86:87], v[74:75], v[140:141] op_sel_hi:[1,0,1]
	v_pk_fma_f32 v[56:57], v[86:87], v[74:75], v[142:143] op_sel:[0,1,0]
	v_pk_fma_f32 v[66:67], v[86:87], v[76:77], v[144:145] op_sel_hi:[1,0,1]
	v_pk_fma_f32 v[68:69], v[86:87], v[76:77], v[146:147] op_sel:[0,1,0]
	ds_read_b128 v[74:77], v121 offset:38912
	s_waitcnt lgkmcnt(7)
	v_pk_mul_f32 v[148:149], v[54:55], v[78:79] op_sel_hi:[1,0]
	v_pk_fma_f32 v[148:149], v[56:57], v[78:79], v[148:149] op_sel:[0,1,0]
	v_pk_fma_f32 v[148:149], v[66:67], v[80:81], v[148:149] op_sel_hi:[1,0,1]
	v_pk_fma_f32 v[148:149], v[68:69], v[80:81], v[148:149] op_sel:[0,1,0]
	ds_read_b128 v[78:81], v121 offset:6144
	s_waitcnt lgkmcnt(7)
	v_pk_mul_f32 v[84:85], v[54:55], v[58:59] op_sel_hi:[1,0]
	v_pk_fma_f32 v[84:85], v[56:57], v[58:59], v[84:85] op_sel:[0,1,0]
	v_pk_fma_f32 v[84:85], v[66:67], v[60:61], v[84:85] op_sel_hi:[1,0,1]
	v_pk_fma_f32 v[84:85], v[68:69], v[60:61], v[84:85] op_sel:[0,1,0]
	ds_read_b128 v[58:61], v121 offset:30976
	v_add_f32_dpp v88, v149, v148 quad_perm:[1,0,3,2] row_mask:0xf bank_mask:0xf bound_ctrl:1
	s_waitcnt lgkmcnt(5)
	v_pk_mul_f32 v[140:141], v[82:83], v[62:63] op_sel_hi:[1,0]
	v_add_f32_dpp v86, v85, v84 quad_perm:[1,0,3,2] row_mask:0xf bank_mask:0xf bound_ctrl:1
	v_pk_mul_f32 v[142:143], v[82:83], v[62:63] op_sel:[0,1]
	v_add_f32_dpp v88, v88, v88 quad_perm:[2,3,0,1] row_mask:0xf bank_mask:0xf bound_ctrl:1
	v_pk_mul_f32 v[144:145], v[82:83], v[64:65] op_sel_hi:[1,0]
	v_add_f32_dpp v86, v86, v86 quad_perm:[2,3,0,1] row_mask:0xf bank_mask:0xf bound_ctrl:1
	v_pk_mul_f32 v[146:147], v[82:83], v[64:65] op_sel:[0,1]
	ds_read_b128 v[62:65], v121 offset:22784
	ds_read_b32 v82, v123 offset:44160
	ds_read_b32 v83, v89 offset:44160
	v_add_f32_dpp v88, v88, v88 row_ror:4 row_mask:0xf bank_mask:0xf bound_ctrl:1
	s_waitcnt lgkmcnt(7)
	v_pk_fma_f32 v[140:141], v[54:55], v[70:71], v[140:141] op_sel_hi:[1,0,1]
	v_add_f32_dpp v86, v86, v86 row_ror:4 row_mask:0xf bank_mask:0xf bound_ctrl:1
	v_pk_fma_f32 v[142:143], v[56:57], v[70:71], v[142:143] op_sel:[0,1,0]
	v_add_f32_dpp v88, v88, v88 row_ror:8 row_mask:0xf bank_mask:0xf bound_ctrl:1
	v_pk_fma_f32 v[144:145], v[66:67], v[72:73], v[144:145] op_sel_hi:[1,0,1]
	v_add_f32_dpp v86, v86, v86 row_ror:8 row_mask:0xf bank_mask:0xf bound_ctrl:1
	v_pk_fma_f32 v[146:147], v[68:69], v[72:73], v[146:147] op_sel:[0,1,0]
	ds_read_b128 v[70:73], v121 offset:14592
	ds_write_b32 v123, v88 offset:48000
	v_mov_b32_dpp v87, v86 quad_perm:[1,0,3,2] row_mask:0xf bank_mask:0xf bound_ctrl:1
	s_waitcnt lgkmcnt(7)
	v_pk_fma_f32 v[54:55], v[86:87], v[74:75], v[140:141] op_sel_hi:[1,0,1]
	v_pk_fma_f32 v[56:57], v[86:87], v[74:75], v[142:143] op_sel:[0,1,0]
	v_pk_fma_f32 v[66:67], v[86:87], v[76:77], v[144:145] op_sel_hi:[1,0,1]
	v_pk_fma_f32 v[68:69], v[86:87], v[76:77], v[146:147] op_sel:[0,1,0]
	ds_read_b128 v[74:77], v121 offset:39168
	s_waitcnt lgkmcnt(7)
	v_pk_mul_f32 v[148:149], v[54:55], v[78:79] op_sel_hi:[1,0]
	v_pk_fma_f32 v[148:149], v[56:57], v[78:79], v[148:149] op_sel:[0,1,0]
	v_pk_fma_f32 v[148:149], v[66:67], v[80:81], v[148:149] op_sel_hi:[1,0,1]
	v_pk_fma_f32 v[148:149], v[68:69], v[80:81], v[148:149] op_sel:[0,1,0]
	ds_read_b128 v[78:81], v121 offset:6400
	s_waitcnt lgkmcnt(7)
	v_pk_mul_f32 v[84:85], v[54:55], v[58:59] op_sel_hi:[1,0]
	v_pk_fma_f32 v[84:85], v[56:57], v[58:59], v[84:85] op_sel:[0,1,0]
	v_pk_fma_f32 v[84:85], v[66:67], v[60:61], v[84:85] op_sel_hi:[1,0,1]
	v_pk_fma_f32 v[84:85], v[68:69], v[60:61], v[84:85] op_sel:[0,1,0]
	ds_read_b128 v[58:61], v121 offset:31232
	v_add_f32_dpp v88, v149, v148 quad_perm:[1,0,3,2] row_mask:0xf bank_mask:0xf bound_ctrl:1
	s_waitcnt lgkmcnt(5)
	v_pk_mul_f32 v[140:141], v[82:83], v[62:63] op_sel_hi:[1,0]
	v_add_f32_dpp v86, v85, v84 quad_perm:[1,0,3,2] row_mask:0xf bank_mask:0xf bound_ctrl:1
	v_pk_mul_f32 v[142:143], v[82:83], v[62:63] op_sel:[0,1]
	v_add_f32_dpp v88, v88, v88 quad_perm:[2,3,0,1] row_mask:0xf bank_mask:0xf bound_ctrl:1
	v_pk_mul_f32 v[144:145], v[82:83], v[64:65] op_sel_hi:[1,0]
	v_add_f32_dpp v86, v86, v86 quad_perm:[2,3,0,1] row_mask:0xf bank_mask:0xf bound_ctrl:1
	v_pk_mul_f32 v[146:147], v[82:83], v[64:65] op_sel:[0,1]
	ds_read_b128 v[62:65], v121 offset:23040
	ds_read_b32 v82, v123 offset:44288
	ds_read_b32 v83, v89 offset:44288
	v_add_f32_dpp v88, v88, v88 row_ror:4 row_mask:0xf bank_mask:0xf bound_ctrl:1
	s_waitcnt lgkmcnt(7)
	v_pk_fma_f32 v[140:141], v[54:55], v[70:71], v[140:141] op_sel_hi:[1,0,1]
	v_add_f32_dpp v86, v86, v86 row_ror:4 row_mask:0xf bank_mask:0xf bound_ctrl:1
	v_pk_fma_f32 v[142:143], v[56:57], v[70:71], v[142:143] op_sel:[0,1,0]
	v_add_f32_dpp v88, v88, v88 row_ror:8 row_mask:0xf bank_mask:0xf bound_ctrl:1
	v_pk_fma_f32 v[144:145], v[66:67], v[72:73], v[144:145] op_sel_hi:[1,0,1]
	v_add_f32_dpp v86, v86, v86 row_ror:8 row_mask:0xf bank_mask:0xf bound_ctrl:1
	v_pk_fma_f32 v[146:147], v[68:69], v[72:73], v[146:147] op_sel:[0,1,0]
	ds_read_b128 v[70:73], v121 offset:14848
	ds_write_b32 v123, v88 offset:48128
	v_mov_b32_dpp v87, v86 quad_perm:[1,0,3,2] row_mask:0xf bank_mask:0xf bound_ctrl:1
	s_waitcnt lgkmcnt(7)
	v_pk_fma_f32 v[54:55], v[86:87], v[74:75], v[140:141] op_sel_hi:[1,0,1]
	v_pk_fma_f32 v[56:57], v[86:87], v[74:75], v[142:143] op_sel:[0,1,0]
	v_pk_fma_f32 v[66:67], v[86:87], v[76:77], v[144:145] op_sel_hi:[1,0,1]
	v_pk_fma_f32 v[68:69], v[86:87], v[76:77], v[146:147] op_sel:[0,1,0]
	ds_read_b128 v[74:77], v121 offset:39424
	s_waitcnt lgkmcnt(7)
	v_pk_mul_f32 v[148:149], v[54:55], v[78:79] op_sel_hi:[1,0]
	v_pk_fma_f32 v[148:149], v[56:57], v[78:79], v[148:149] op_sel:[0,1,0]
	v_pk_fma_f32 v[148:149], v[66:67], v[80:81], v[148:149] op_sel_hi:[1,0,1]
	v_pk_fma_f32 v[148:149], v[68:69], v[80:81], v[148:149] op_sel:[0,1,0]
	ds_read_b128 v[78:81], v121 offset:6656
	s_waitcnt lgkmcnt(7)
	v_pk_mul_f32 v[84:85], v[54:55], v[58:59] op_sel_hi:[1,0]
	v_pk_fma_f32 v[84:85], v[56:57], v[58:59], v[84:85] op_sel:[0,1,0]
	v_pk_fma_f32 v[84:85], v[66:67], v[60:61], v[84:85] op_sel_hi:[1,0,1]
	v_pk_fma_f32 v[84:85], v[68:69], v[60:61], v[84:85] op_sel:[0,1,0]
	ds_read_b128 v[58:61], v121 offset:31488
	v_add_f32_dpp v88, v149, v148 quad_perm:[1,0,3,2] row_mask:0xf bank_mask:0xf bound_ctrl:1
	s_waitcnt lgkmcnt(5)
	v_pk_mul_f32 v[140:141], v[82:83], v[62:63] op_sel_hi:[1,0]
	v_add_f32_dpp v86, v85, v84 quad_perm:[1,0,3,2] row_mask:0xf bank_mask:0xf bound_ctrl:1
	v_pk_mul_f32 v[142:143], v[82:83], v[62:63] op_sel:[0,1]
	v_add_f32_dpp v88, v88, v88 quad_perm:[2,3,0,1] row_mask:0xf bank_mask:0xf bound_ctrl:1
	v_pk_mul_f32 v[144:145], v[82:83], v[64:65] op_sel_hi:[1,0]
	v_add_f32_dpp v86, v86, v86 quad_perm:[2,3,0,1] row_mask:0xf bank_mask:0xf bound_ctrl:1
	v_pk_mul_f32 v[146:147], v[82:83], v[64:65] op_sel:[0,1]
	ds_read_b128 v[62:65], v121 offset:23296
	ds_read_b32 v82, v123 offset:44416
	ds_read_b32 v83, v89 offset:44416
	v_add_f32_dpp v88, v88, v88 row_ror:4 row_mask:0xf bank_mask:0xf bound_ctrl:1
	s_waitcnt lgkmcnt(7)
	v_pk_fma_f32 v[140:141], v[54:55], v[70:71], v[140:141] op_sel_hi:[1,0,1]
	v_add_f32_dpp v86, v86, v86 row_ror:4 row_mask:0xf bank_mask:0xf bound_ctrl:1
	v_pk_fma_f32 v[142:143], v[56:57], v[70:71], v[142:143] op_sel:[0,1,0]
	v_add_f32_dpp v88, v88, v88 row_ror:8 row_mask:0xf bank_mask:0xf bound_ctrl:1
	v_pk_fma_f32 v[144:145], v[66:67], v[72:73], v[144:145] op_sel_hi:[1,0,1]
	v_add_f32_dpp v86, v86, v86 row_ror:8 row_mask:0xf bank_mask:0xf bound_ctrl:1
	v_pk_fma_f32 v[146:147], v[68:69], v[72:73], v[146:147] op_sel:[0,1,0]
	ds_read_b128 v[70:73], v121 offset:15104
	ds_write_b32 v123, v88 offset:48256
	v_mov_b32_dpp v87, v86 quad_perm:[1,0,3,2] row_mask:0xf bank_mask:0xf bound_ctrl:1
	s_waitcnt lgkmcnt(7)
	v_pk_fma_f32 v[54:55], v[86:87], v[74:75], v[140:141] op_sel_hi:[1,0,1]
	v_pk_fma_f32 v[56:57], v[86:87], v[74:75], v[142:143] op_sel:[0,1,0]
	v_pk_fma_f32 v[66:67], v[86:87], v[76:77], v[144:145] op_sel_hi:[1,0,1]
	v_pk_fma_f32 v[68:69], v[86:87], v[76:77], v[146:147] op_sel:[0,1,0]
	ds_read_b128 v[74:77], v121 offset:39680
	s_waitcnt lgkmcnt(7)
	v_pk_mul_f32 v[148:149], v[54:55], v[78:79] op_sel_hi:[1,0]
	v_pk_fma_f32 v[148:149], v[56:57], v[78:79], v[148:149] op_sel:[0,1,0]
	v_pk_fma_f32 v[148:149], v[66:67], v[80:81], v[148:149] op_sel_hi:[1,0,1]
	v_pk_fma_f32 v[148:149], v[68:69], v[80:81], v[148:149] op_sel:[0,1,0]
	ds_read_b128 v[78:81], v121 offset:6912
	s_waitcnt lgkmcnt(7)
	v_pk_mul_f32 v[84:85], v[54:55], v[58:59] op_sel_hi:[1,0]
	v_pk_fma_f32 v[84:85], v[56:57], v[58:59], v[84:85] op_sel:[0,1,0]
	v_pk_fma_f32 v[84:85], v[66:67], v[60:61], v[84:85] op_sel_hi:[1,0,1]
	v_pk_fma_f32 v[84:85], v[68:69], v[60:61], v[84:85] op_sel:[0,1,0]
	ds_read_b128 v[58:61], v121 offset:31744
	v_add_f32_dpp v88, v149, v148 quad_perm:[1,0,3,2] row_mask:0xf bank_mask:0xf bound_ctrl:1
	s_waitcnt lgkmcnt(5)
	v_pk_mul_f32 v[140:141], v[82:83], v[62:63] op_sel_hi:[1,0]
	v_add_f32_dpp v86, v85, v84 quad_perm:[1,0,3,2] row_mask:0xf bank_mask:0xf bound_ctrl:1
	v_pk_mul_f32 v[142:143], v[82:83], v[62:63] op_sel:[0,1]
	v_add_f32_dpp v88, v88, v88 quad_perm:[2,3,0,1] row_mask:0xf bank_mask:0xf bound_ctrl:1
	v_pk_mul_f32 v[144:145], v[82:83], v[64:65] op_sel_hi:[1,0]
	v_add_f32_dpp v86, v86, v86 quad_perm:[2,3,0,1] row_mask:0xf bank_mask:0xf bound_ctrl:1
	v_pk_mul_f32 v[146:147], v[82:83], v[64:65] op_sel:[0,1]
	ds_read_b128 v[62:65], v121 offset:23552
	ds_read_b32 v82, v123 offset:44544
	ds_read_b32 v83, v89 offset:44544
	v_add_f32_dpp v88, v88, v88 row_ror:4 row_mask:0xf bank_mask:0xf bound_ctrl:1
	s_waitcnt lgkmcnt(7)
	v_pk_fma_f32 v[140:141], v[54:55], v[70:71], v[140:141] op_sel_hi:[1,0,1]
	v_add_f32_dpp v86, v86, v86 row_ror:4 row_mask:0xf bank_mask:0xf bound_ctrl:1
	v_pk_fma_f32 v[142:143], v[56:57], v[70:71], v[142:143] op_sel:[0,1,0]
	v_add_f32_dpp v88, v88, v88 row_ror:8 row_mask:0xf bank_mask:0xf bound_ctrl:1
	v_pk_fma_f32 v[144:145], v[66:67], v[72:73], v[144:145] op_sel_hi:[1,0,1]
	v_add_f32_dpp v86, v86, v86 row_ror:8 row_mask:0xf bank_mask:0xf bound_ctrl:1
	v_pk_fma_f32 v[146:147], v[68:69], v[72:73], v[146:147] op_sel:[0,1,0]
	ds_read_b128 v[70:73], v121 offset:15360
	ds_write_b32 v123, v88 offset:48384
	v_mov_b32_dpp v87, v86 quad_perm:[1,0,3,2] row_mask:0xf bank_mask:0xf bound_ctrl:1
	s_waitcnt lgkmcnt(7)
	v_pk_fma_f32 v[54:55], v[86:87], v[74:75], v[140:141] op_sel_hi:[1,0,1]
	v_pk_fma_f32 v[56:57], v[86:87], v[74:75], v[142:143] op_sel:[0,1,0]
	v_pk_fma_f32 v[66:67], v[86:87], v[76:77], v[144:145] op_sel_hi:[1,0,1]
	v_pk_fma_f32 v[68:69], v[86:87], v[76:77], v[146:147] op_sel:[0,1,0]
	ds_read_b128 v[74:77], v121 offset:39936
	s_waitcnt lgkmcnt(7)
	v_pk_mul_f32 v[148:149], v[54:55], v[78:79] op_sel_hi:[1,0]
	v_pk_fma_f32 v[148:149], v[56:57], v[78:79], v[148:149] op_sel:[0,1,0]
	v_pk_fma_f32 v[148:149], v[66:67], v[80:81], v[148:149] op_sel_hi:[1,0,1]
	v_pk_fma_f32 v[148:149], v[68:69], v[80:81], v[148:149] op_sel:[0,1,0]
	ds_read_b128 v[78:81], v121 offset:7168
	s_waitcnt lgkmcnt(7)
	v_pk_mul_f32 v[84:85], v[54:55], v[58:59] op_sel_hi:[1,0]
	v_pk_fma_f32 v[84:85], v[56:57], v[58:59], v[84:85] op_sel:[0,1,0]
	v_pk_fma_f32 v[84:85], v[66:67], v[60:61], v[84:85] op_sel_hi:[1,0,1]
	v_pk_fma_f32 v[84:85], v[68:69], v[60:61], v[84:85] op_sel:[0,1,0]
	ds_read_b128 v[58:61], v121 offset:32000
	v_add_f32_dpp v88, v149, v148 quad_perm:[1,0,3,2] row_mask:0xf bank_mask:0xf bound_ctrl:1
	s_waitcnt lgkmcnt(5)
	v_pk_mul_f32 v[140:141], v[82:83], v[62:63] op_sel_hi:[1,0]
	v_add_f32_dpp v86, v85, v84 quad_perm:[1,0,3,2] row_mask:0xf bank_mask:0xf bound_ctrl:1
	v_pk_mul_f32 v[142:143], v[82:83], v[62:63] op_sel:[0,1]
	v_add_f32_dpp v88, v88, v88 quad_perm:[2,3,0,1] row_mask:0xf bank_mask:0xf bound_ctrl:1
	v_pk_mul_f32 v[144:145], v[82:83], v[64:65] op_sel_hi:[1,0]
	v_add_f32_dpp v86, v86, v86 quad_perm:[2,3,0,1] row_mask:0xf bank_mask:0xf bound_ctrl:1
	v_pk_mul_f32 v[146:147], v[82:83], v[64:65] op_sel:[0,1]
	ds_read_b128 v[62:65], v121 offset:23808
	ds_read_b32 v82, v123 offset:44672
	ds_read_b32 v83, v89 offset:44672
	v_add_f32_dpp v88, v88, v88 row_ror:4 row_mask:0xf bank_mask:0xf bound_ctrl:1
	s_waitcnt lgkmcnt(7)
	v_pk_fma_f32 v[140:141], v[54:55], v[70:71], v[140:141] op_sel_hi:[1,0,1]
	v_add_f32_dpp v86, v86, v86 row_ror:4 row_mask:0xf bank_mask:0xf bound_ctrl:1
	v_pk_fma_f32 v[142:143], v[56:57], v[70:71], v[142:143] op_sel:[0,1,0]
	v_add_f32_dpp v88, v88, v88 row_ror:8 row_mask:0xf bank_mask:0xf bound_ctrl:1
	v_pk_fma_f32 v[144:145], v[66:67], v[72:73], v[144:145] op_sel_hi:[1,0,1]
	v_add_f32_dpp v86, v86, v86 row_ror:8 row_mask:0xf bank_mask:0xf bound_ctrl:1
	v_pk_fma_f32 v[146:147], v[68:69], v[72:73], v[146:147] op_sel:[0,1,0]
	ds_read_b128 v[70:73], v121 offset:15616
	ds_write_b32 v123, v88 offset:48512
	v_mov_b32_dpp v87, v86 quad_perm:[1,0,3,2] row_mask:0xf bank_mask:0xf bound_ctrl:1
	s_waitcnt lgkmcnt(7)
	v_pk_fma_f32 v[54:55], v[86:87], v[74:75], v[140:141] op_sel_hi:[1,0,1]
	v_pk_fma_f32 v[56:57], v[86:87], v[74:75], v[142:143] op_sel:[0,1,0]
	v_pk_fma_f32 v[66:67], v[86:87], v[76:77], v[144:145] op_sel_hi:[1,0,1]
	v_pk_fma_f32 v[68:69], v[86:87], v[76:77], v[146:147] op_sel:[0,1,0]
	ds_read_b128 v[74:77], v121 offset:40192
	s_waitcnt lgkmcnt(7)
	v_pk_mul_f32 v[148:149], v[54:55], v[78:79] op_sel_hi:[1,0]
	v_pk_fma_f32 v[148:149], v[56:57], v[78:79], v[148:149] op_sel:[0,1,0]
	v_pk_fma_f32 v[148:149], v[66:67], v[80:81], v[148:149] op_sel_hi:[1,0,1]
	v_pk_fma_f32 v[148:149], v[68:69], v[80:81], v[148:149] op_sel:[0,1,0]
	ds_read_b128 v[78:81], v121 offset:7424
	s_waitcnt lgkmcnt(7)
	v_pk_mul_f32 v[84:85], v[54:55], v[58:59] op_sel_hi:[1,0]
	v_pk_fma_f32 v[84:85], v[56:57], v[58:59], v[84:85] op_sel:[0,1,0]
	v_pk_fma_f32 v[84:85], v[66:67], v[60:61], v[84:85] op_sel_hi:[1,0,1]
	v_pk_fma_f32 v[84:85], v[68:69], v[60:61], v[84:85] op_sel:[0,1,0]
	ds_read_b128 v[58:61], v121 offset:32256
	v_add_f32_dpp v88, v149, v148 quad_perm:[1,0,3,2] row_mask:0xf bank_mask:0xf bound_ctrl:1
	s_waitcnt lgkmcnt(5)
	v_pk_mul_f32 v[140:141], v[82:83], v[62:63] op_sel_hi:[1,0]
	v_add_f32_dpp v86, v85, v84 quad_perm:[1,0,3,2] row_mask:0xf bank_mask:0xf bound_ctrl:1
	v_pk_mul_f32 v[142:143], v[82:83], v[62:63] op_sel:[0,1]
	v_add_f32_dpp v88, v88, v88 quad_perm:[2,3,0,1] row_mask:0xf bank_mask:0xf bound_ctrl:1
	v_pk_mul_f32 v[144:145], v[82:83], v[64:65] op_sel_hi:[1,0]
	v_add_f32_dpp v86, v86, v86 quad_perm:[2,3,0,1] row_mask:0xf bank_mask:0xf bound_ctrl:1
	v_pk_mul_f32 v[146:147], v[82:83], v[64:65] op_sel:[0,1]
	ds_read_b128 v[62:65], v121 offset:24064
	ds_read_b32 v82, v123 offset:44800
	ds_read_b32 v83, v89 offset:44800
	v_add_f32_dpp v88, v88, v88 row_ror:4 row_mask:0xf bank_mask:0xf bound_ctrl:1
	s_waitcnt lgkmcnt(7)
	v_pk_fma_f32 v[140:141], v[54:55], v[70:71], v[140:141] op_sel_hi:[1,0,1]
	v_add_f32_dpp v86, v86, v86 row_ror:4 row_mask:0xf bank_mask:0xf bound_ctrl:1
	v_pk_fma_f32 v[142:143], v[56:57], v[70:71], v[142:143] op_sel:[0,1,0]
	v_add_f32_dpp v88, v88, v88 row_ror:8 row_mask:0xf bank_mask:0xf bound_ctrl:1
	v_pk_fma_f32 v[144:145], v[66:67], v[72:73], v[144:145] op_sel_hi:[1,0,1]
	v_add_f32_dpp v86, v86, v86 row_ror:8 row_mask:0xf bank_mask:0xf bound_ctrl:1
	v_pk_fma_f32 v[146:147], v[68:69], v[72:73], v[146:147] op_sel:[0,1,0]
	ds_read_b128 v[70:73], v121 offset:15872
	ds_write_b32 v123, v88 offset:48640
	v_mov_b32_dpp v87, v86 quad_perm:[1,0,3,2] row_mask:0xf bank_mask:0xf bound_ctrl:1
	s_waitcnt lgkmcnt(7)
	v_pk_fma_f32 v[54:55], v[86:87], v[74:75], v[140:141] op_sel_hi:[1,0,1]
	v_pk_fma_f32 v[56:57], v[86:87], v[74:75], v[142:143] op_sel:[0,1,0]
	v_pk_fma_f32 v[66:67], v[86:87], v[76:77], v[144:145] op_sel_hi:[1,0,1]
	v_pk_fma_f32 v[68:69], v[86:87], v[76:77], v[146:147] op_sel:[0,1,0]
	ds_read_b128 v[74:77], v121 offset:40448
	s_waitcnt lgkmcnt(7)
	v_pk_mul_f32 v[148:149], v[54:55], v[78:79] op_sel_hi:[1,0]
	v_pk_fma_f32 v[148:149], v[56:57], v[78:79], v[148:149] op_sel:[0,1,0]
	v_pk_fma_f32 v[148:149], v[66:67], v[80:81], v[148:149] op_sel_hi:[1,0,1]
	v_pk_fma_f32 v[148:149], v[68:69], v[80:81], v[148:149] op_sel:[0,1,0]
	ds_read_b128 v[78:81], v121 offset:7680
	s_waitcnt lgkmcnt(7)
	v_pk_mul_f32 v[84:85], v[54:55], v[58:59] op_sel_hi:[1,0]
	v_pk_fma_f32 v[84:85], v[56:57], v[58:59], v[84:85] op_sel:[0,1,0]
	v_pk_fma_f32 v[84:85], v[66:67], v[60:61], v[84:85] op_sel_hi:[1,0,1]
	v_pk_fma_f32 v[84:85], v[68:69], v[60:61], v[84:85] op_sel:[0,1,0]
	ds_read_b128 v[58:61], v121 offset:32512
	v_add_f32_dpp v88, v149, v148 quad_perm:[1,0,3,2] row_mask:0xf bank_mask:0xf bound_ctrl:1
	s_waitcnt lgkmcnt(5)
	v_pk_mul_f32 v[140:141], v[82:83], v[62:63] op_sel_hi:[1,0]
	v_add_f32_dpp v86, v85, v84 quad_perm:[1,0,3,2] row_mask:0xf bank_mask:0xf bound_ctrl:1
	v_pk_mul_f32 v[142:143], v[82:83], v[62:63] op_sel:[0,1]
	v_add_f32_dpp v88, v88, v88 quad_perm:[2,3,0,1] row_mask:0xf bank_mask:0xf bound_ctrl:1
	v_pk_mul_f32 v[144:145], v[82:83], v[64:65] op_sel_hi:[1,0]
	v_add_f32_dpp v86, v86, v86 quad_perm:[2,3,0,1] row_mask:0xf bank_mask:0xf bound_ctrl:1
	v_pk_mul_f32 v[146:147], v[82:83], v[64:65] op_sel:[0,1]
	ds_read_b128 v[62:65], v121 offset:24320
	ds_read_b32 v82, v123 offset:44928
	ds_read_b32 v83, v89 offset:44928
	v_add_f32_dpp v88, v88, v88 row_ror:4 row_mask:0xf bank_mask:0xf bound_ctrl:1
	s_waitcnt lgkmcnt(7)
	v_pk_fma_f32 v[140:141], v[54:55], v[70:71], v[140:141] op_sel_hi:[1,0,1]
	v_add_f32_dpp v86, v86, v86 row_ror:4 row_mask:0xf bank_mask:0xf bound_ctrl:1
	v_pk_fma_f32 v[142:143], v[56:57], v[70:71], v[142:143] op_sel:[0,1,0]
	v_add_f32_dpp v88, v88, v88 row_ror:8 row_mask:0xf bank_mask:0xf bound_ctrl:1
	v_pk_fma_f32 v[144:145], v[66:67], v[72:73], v[144:145] op_sel_hi:[1,0,1]
	v_add_f32_dpp v86, v86, v86 row_ror:8 row_mask:0xf bank_mask:0xf bound_ctrl:1
	v_pk_fma_f32 v[146:147], v[68:69], v[72:73], v[146:147] op_sel:[0,1,0]
	ds_read_b128 v[70:73], v121 offset:16128
	ds_write_b32 v123, v88 offset:48768
	v_mov_b32_dpp v87, v86 quad_perm:[1,0,3,2] row_mask:0xf bank_mask:0xf bound_ctrl:1
	s_waitcnt lgkmcnt(7)
	v_pk_fma_f32 v[54:55], v[86:87], v[74:75], v[140:141] op_sel_hi:[1,0,1]
	v_pk_fma_f32 v[56:57], v[86:87], v[74:75], v[142:143] op_sel:[0,1,0]
	v_pk_fma_f32 v[66:67], v[86:87], v[76:77], v[144:145] op_sel_hi:[1,0,1]
	v_pk_fma_f32 v[68:69], v[86:87], v[76:77], v[146:147] op_sel:[0,1,0]
	ds_read_b128 v[74:77], v121 offset:40704
	s_waitcnt lgkmcnt(7)
	v_pk_mul_f32 v[148:149], v[54:55], v[78:79] op_sel_hi:[1,0]
	v_pk_fma_f32 v[148:149], v[56:57], v[78:79], v[148:149] op_sel:[0,1,0]
	v_pk_fma_f32 v[148:149], v[66:67], v[80:81], v[148:149] op_sel_hi:[1,0,1]
	v_pk_fma_f32 v[148:149], v[68:69], v[80:81], v[148:149] op_sel:[0,1,0]
	ds_read_b128 v[78:81], v121 offset:7936
	s_waitcnt lgkmcnt(7)
	v_pk_mul_f32 v[84:85], v[54:55], v[58:59] op_sel_hi:[1,0]
	v_pk_fma_f32 v[84:85], v[56:57], v[58:59], v[84:85] op_sel:[0,1,0]
	v_pk_fma_f32 v[84:85], v[66:67], v[60:61], v[84:85] op_sel_hi:[1,0,1]
	v_pk_fma_f32 v[84:85], v[68:69], v[60:61], v[84:85] op_sel:[0,1,0]
	v_add_f32_dpp v88, v149, v148 quad_perm:[1,0,3,2] row_mask:0xf bank_mask:0xf bound_ctrl:1
	s_waitcnt lgkmcnt(4)
	v_pk_mul_f32 v[140:141], v[82:83], v[62:63] op_sel_hi:[1,0]
	v_add_f32_dpp v86, v85, v84 quad_perm:[1,0,3,2] row_mask:0xf bank_mask:0xf bound_ctrl:1
	v_pk_mul_f32 v[142:143], v[82:83], v[62:63] op_sel:[0,1]
	v_add_f32_dpp v88, v88, v88 quad_perm:[2,3,0,1] row_mask:0xf bank_mask:0xf bound_ctrl:1
	v_pk_mul_f32 v[144:145], v[82:83], v[64:65] op_sel_hi:[1,0]
	v_add_f32_dpp v86, v86, v86 quad_perm:[2,3,0,1] row_mask:0xf bank_mask:0xf bound_ctrl:1
	v_pk_mul_f32 v[146:147], v[82:83], v[64:65] op_sel:[0,1]
	v_add_f32_dpp v88, v88, v88 row_ror:4 row_mask:0xf bank_mask:0xf bound_ctrl:1
	s_waitcnt lgkmcnt(3)
	v_pk_fma_f32 v[140:141], v[54:55], v[70:71], v[140:141] op_sel_hi:[1,0,1]
	v_add_f32_dpp v86, v86, v86 row_ror:4 row_mask:0xf bank_mask:0xf bound_ctrl:1
	v_pk_fma_f32 v[142:143], v[56:57], v[70:71], v[142:143] op_sel:[0,1,0]
	v_add_f32_dpp v88, v88, v88 row_ror:8 row_mask:0xf bank_mask:0xf bound_ctrl:1
	v_pk_fma_f32 v[144:145], v[66:67], v[72:73], v[144:145] op_sel_hi:[1,0,1]
	v_add_f32_dpp v86, v86, v86 row_ror:8 row_mask:0xf bank_mask:0xf bound_ctrl:1
	v_pk_fma_f32 v[146:147], v[68:69], v[72:73], v[146:147] op_sel:[0,1,0]
	ds_write_b32 v123, v88 offset:48896
	v_mov_b32_dpp v87, v86 quad_perm:[1,0,3,2] row_mask:0xf bank_mask:0xf bound_ctrl:1
	s_waitcnt lgkmcnt(2)
	v_pk_fma_f32 v[54:55], v[86:87], v[74:75], v[140:141] op_sel_hi:[1,0,1]
	v_pk_fma_f32 v[56:57], v[86:87], v[74:75], v[142:143] op_sel:[0,1,0]
	v_pk_fma_f32 v[66:67], v[86:87], v[76:77], v[144:145] op_sel_hi:[1,0,1]
	v_pk_fma_f32 v[68:69], v[86:87], v[76:77], v[146:147] op_sel:[0,1,0]
	s_waitcnt lgkmcnt(1)
	v_pk_mul_f32 v[148:149], v[54:55], v[78:79] op_sel_hi:[1,0]
	v_pk_fma_f32 v[148:149], v[56:57], v[78:79], v[148:149] op_sel:[0,1,0]
	v_pk_fma_f32 v[148:149], v[66:67], v[80:81], v[148:149] op_sel_hi:[1,0,1]
	v_pk_fma_f32 v[148:149], v[68:69], v[80:81], v[148:149] op_sel:[0,1,0]
	s_nop 1
	v_add_f32_dpp v88, v149, v148 quad_perm:[1,0,3,2] row_mask:0xf bank_mask:0xf bound_ctrl:1
	s_nop 1
	v_add_f32_dpp v88, v88, v88 quad_perm:[2,3,0,1] row_mask:0xf bank_mask:0xf bound_ctrl:1
	s_nop 1
	v_add_f32_dpp v88, v88, v88 row_ror:4 row_mask:0xf bank_mask:0xf bound_ctrl:1
	s_nop 1
	v_add_f32_dpp v88, v88, v88 row_ror:8 row_mask:0xf bank_mask:0xf bound_ctrl:1
	ds_write_b32 v123, v88 offset:49024
	s_branch .LBB0_1842

.LBB0_2811:
	s_cmp_lt_i32 s86, 18
	s_cselect_b64 s[2:3], -1, 0
	s_and_b64 s[0:1], s[2:3], s[0:1]
	s_andn2_b64 vcc, exec, s[0:1]
	s_cbranch_vccnz .LBB0_2815
	s_cmpk_gt_i32 s88, 0x7fff
	s_cbranch_scc1 .LBB0_2815
	v_lshlrev_b32_e32 v16, 4, v152
	global_load_dwordx4 v[0:3], v16, s[72:73]
	global_load_dwordx4 v[4:7], v16, s[72:73] offset:1024
	global_load_dwordx4 v[8:11], v16, s[72:73] offset:2048
	global_load_dwordx4 v[12:15], v16, s[72:73] offset:3072
	s_ashr_i32 s89, s88, 31
	s_ashr_i32 s95, s94, 31
	s_lshl_b64 s[6:7], s[88:89], 11
	s_lshl_b64 s[0:1], s[88:89], 6
	s_lshl_b64 s[4:5], s[94:95], 6
	v_lshl_or_b32 v18, v152, 3, s6
	v_mov_b32_e32 v19, s7
	s_lshl_b64 s[6:7], s[94:95], 11
	s_lshl_b64 s[8:9], s[88:89], 12
	s_add_u32 s8, s74, s8
	v_mov_b32_e32 v17, 0
	s_addc_u32 s9, s75, s9
	v_lshl_add_u64 v[20:21], s[8:9], 0, v[16:17]
	s_mov_b64 s[8:9], 0xc00
	v_lshl_add_u64 v[20:21], v[20:21], 0, s[8:9]
	s_lshl_b64 s[8:9], s[94:95], 12
	v_mov_b32_e32 v16, 0x1fd00000
	v_mov_b32_e32 v22, 0x358637bd
	s_mov_b32 s10, 0x800000
	v_lshl_add_u64 v[18:19], s[96:97], 0, v[18:19]
	s_mov_b32 s20, 0x3000000
	s_mov_b32 s21, 0
	v_lshl_add_u64 v[18:19], v[18:19], 0, s[20:21]
	s_add_u32 s12, s96, s0
	s_addc_u32 s13, s97, s1
	s_add_u32 s12, s12, 0x1fd00000
	s_addc_u32 s13, s13, 0
	s_mov_b32 s22, s88
	global_load_dwordx2 v[56:57], v[18:19], off
	global_load_dwordx2 v[58:59], v[18:19], off offset:512
	global_load_dwordx2 v[60:61], v[18:19], off offset:1024
	global_load_dwordx2 v[62:63], v[18:19], off offset:1536
	global_load_dwordx4 v[64:67], v17, s[12:13] offset:48
	global_load_dwordx4 v[68:71], v17, s[12:13] offset:32
	global_load_dwordx4 v[72:75], v17, s[12:13] offset:16
	global_load_dwordx4 v[76:79], v17, s[12:13]
	s_add_i32 s22, s22, s94
	s_cmp_lt_i32 s22, 0x8000
	s_cselect_b32 s24, s6, 0
	s_cselect_b32 s25, s7, 0
	s_cselect_b32 s26, s4, 0
	s_cselect_b32 s27, s5, 0
	v_lshl_add_u64 v[18:19], v[18:19], 0, s[24:25]
	s_add_u32 s12, s12, s26
	s_addc_u32 s13, s13, s27
	global_load_dwordx2 v[80:81], v[18:19], off
	global_load_dwordx2 v[82:83], v[18:19], off offset:512
	global_load_dwordx2 v[84:85], v[18:19], off offset:1024
	global_load_dwordx2 v[86:87], v[18:19], off offset:1536
	global_load_dwordx4 v[88:91], v17, s[12:13] offset:48
	global_load_dwordx4 v[92:95], v17, s[12:13] offset:32
	global_load_dwordx4 v[96:99], v17, s[12:13] offset:16
	global_load_dwordx4 v[100:103], v17, s[12:13]
	s_add_i32 s22, s22, s94
	s_cmp_lt_i32 s22, 0x8000
	s_cselect_b32 s24, s6, 0
	s_cselect_b32 s25, s7, 0
	s_cselect_b32 s26, s4, 0
	s_cselect_b32 s27, s5, 0
	v_lshl_add_u64 v[18:19], v[18:19], 0, s[24:25]
	s_add_u32 s12, s12, s26
	s_addc_u32 s13, s13, s27
	global_load_dwordx2 v[104:105], v[18:19], off
	global_load_dwordx2 v[106:107], v[18:19], off offset:512
	global_load_dwordx2 v[108:109], v[18:19], off offset:1024
	global_load_dwordx2 v[110:111], v[18:19], off offset:1536
	global_load_dwordx4 v[112:115], v17, s[12:13] offset:48
	global_load_dwordx4 v[116:119], v17, s[12:13] offset:32
	global_load_dwordx4 v[120:123], v17, s[12:13] offset:16
	global_load_dwordx4 v[124:127], v17, s[12:13]
	s_add_i32 s22, s22, s94
	s_cmp_lt_i32 s22, 0x8000
	s_cselect_b32 s24, s6, 0
	s_cselect_b32 s25, s7, 0
	s_cselect_b32 s26, s4, 0
	s_cselect_b32 s27, s5, 0
	v_lshl_add_u64 v[18:19], v[18:19], 0, s[24:25]
	s_add_u32 s12, s12, s26
	s_addc_u32 s13, s13, s27
	s_waitcnt vmcnt(16)
	v_pk_add_f32 v[74:75], v[78:79], v[74:75]
	v_pk_add_f32 v[72:73], v[76:77], v[72:73]
	v_pk_add_f32 v[70:71], v[74:75], v[70:71]
	v_pk_add_f32 v[68:69], v[72:73], v[68:69]
	v_pk_add_f32 v[66:67], v[70:71], v[66:67]
	v_pk_add_f32 v[64:65], v[68:69], v[64:65]
	v_mov_b32_e32 v69, v66
	v_mov_b32_e32 v68, v65
	v_mov_b32_e32 v65, v67
	v_pk_add_f32 v[64:65], v[68:69], v[64:65]
	v_lshlrev_b32_e32 v128, 16, v56
	v_and_b32_e32 v129, 0xffff0000, v56
	v_lshlrev_b32_e32 v132, 16, v58
	v_and_b32_e32 v133, 0xffff0000, v58
	v_lshlrev_b32_e32 v136, 16, v60
	v_and_b32_e32 v137, 0xffff0000, v60
	v_lshlrev_b32_e32 v140, 16, v62
	v_and_b32_e32 v141, 0xffff0000, v62
	v_add_f32_e32 v23, v64, v65
	v_fmamk_f32 v23, v23, 0x3a800000, v22
	v_mul_f32_e32 v50, 0x4b800000, v23
	v_cmp_gt_f32_e32 vcc, s10, v23
	v_lshlrev_b32_e32 v130, 16, v57
	v_and_b32_e32 v131, 0xffff0000, v57
	v_lshlrev_b32_e32 v134, 16, v59
	v_and_b32_e32 v135, 0xffff0000, v59
	v_cndmask_b32_e32 v23, v23, v50, vcc
	v_rsq_f32_e32 v23, v23
	v_lshlrev_b32_e32 v138, 16, v61
	v_and_b32_e32 v139, 0xffff0000, v61
	v_lshlrev_b32_e32 v142, 16, v63
	v_and_b32_e32 v143, 0xffff0000, v63
	v_mul_f32_e32 v50, 0x45800000, v23
	s_nop 1
	v_cndmask_b32_e32 v50, v23, v50, vcc
	v_pk_mul_f32 v[24:25], v[50:51], v[128:129] op_sel_hi:[0,1]
	v_pk_mul_f32 v[26:27], v[50:51], v[130:131] op_sel_hi:[0,1]
	v_pk_mul_f32 v[28:29], v[50:51], v[132:133] op_sel_hi:[0,1]
	v_pk_mul_f32 v[30:31], v[50:51], v[134:135] op_sel_hi:[0,1]
	v_pk_mul_f32 v[32:33], v[50:51], v[136:137] op_sel_hi:[0,1]
	v_pk_mul_f32 v[34:35], v[50:51], v[138:139] op_sel_hi:[0,1]
	v_pk_mul_f32 v[36:37], v[50:51], v[140:141] op_sel_hi:[0,1]
	v_pk_mul_f32 v[38:39], v[50:51], v[142:143] op_sel_hi:[0,1]
	v_pk_mul_f32 v[24:25], v[0:1], v[24:25]
	v_pk_mul_f32 v[26:27], v[2:3], v[26:27]
	v_pk_mul_f32 v[28:29], v[4:5], v[28:29]
	v_pk_mul_f32 v[30:31], v[6:7], v[30:31]
	v_pk_mul_f32 v[32:33], v[8:9], v[32:33]
	v_pk_mul_f32 v[34:35], v[10:11], v[34:35]
	v_pk_mul_f32 v[36:37], v[12:13], v[36:37]
	v_pk_mul_f32 v[38:39], v[14:15], v[38:39]
	global_store_dwordx4 v[20:21], v[24:27], off offset:-3072
	global_store_dwordx4 v[20:21], v[28:31], off offset:-2048
	global_store_dwordx4 v[20:21], v[32:35], off offset:-1024
	global_store_dwordx4 v[20:21], v[36:39], off
	v_lshl_add_u64 v[20:21], v[20:21], 0, s[8:9]
	s_add_i32 s88, s88, s94
	s_cmp_lt_i32 s88, 0x8000
	s_cbranch_scc0 .Lfn_done
.Lfn_loop:
	global_load_dwordx2 v[56:57], v[18:19], off
	global_load_dwordx2 v[58:59], v[18:19], off offset:512
	global_load_dwordx2 v[60:61], v[18:19], off offset:1024
	global_load_dwordx2 v[62:63], v[18:19], off offset:1536
	global_load_dwordx4 v[64:67], v17, s[12:13] offset:48
	global_load_dwordx4 v[68:71], v17, s[12:13] offset:32
	global_load_dwordx4 v[72:75], v17, s[12:13] offset:16
	global_load_dwordx4 v[76:79], v17, s[12:13]
	s_add_i32 s22, s22, s94
	s_cmp_lt_i32 s22, 0x8000
	s_cselect_b32 s24, s6, 0
	s_cselect_b32 s25, s7, 0
	s_cselect_b32 s26, s4, 0
	s_cselect_b32 s27, s5, 0
	v_lshl_add_u64 v[18:19], v[18:19], 0, s[24:25]
	s_add_u32 s12, s12, s26
	s_addc_u32 s13, s13, s27
	s_waitcnt vmcnt(20)
	v_pk_add_f32 v[98:99], v[102:103], v[98:99]
	v_pk_add_f32 v[96:97], v[100:101], v[96:97]
	v_pk_add_f32 v[94:95], v[98:99], v[94:95]
	v_pk_add_f32 v[92:93], v[96:97], v[92:93]
	v_pk_add_f32 v[90:91], v[94:95], v[90:91]
	v_pk_add_f32 v[88:89], v[92:93], v[88:89]
	v_mov_b32_e32 v93, v90
	v_mov_b32_e32 v92, v89
	v_mov_b32_e32 v89, v91
	v_pk_add_f32 v[88:89], v[92:93], v[88:89]
	v_lshlrev_b32_e32 v128, 16, v80
	v_and_b32_e32 v129, 0xffff0000, v80
	v_lshlrev_b32_e32 v132, 16, v82
	v_and_b32_e32 v133, 0xffff0000, v82
	v_lshlrev_b32_e32 v136, 16, v84
	v_and_b32_e32 v137, 0xffff0000, v84
	v_lshlrev_b32_e32 v140, 16, v86
	v_and_b32_e32 v141, 0xffff0000, v86
	v_add_f32_e32 v23, v88, v89
	v_fmamk_f32 v23, v23, 0x3a800000, v22
	v_mul_f32_e32 v50, 0x4b800000, v23
	v_cmp_gt_f32_e32 vcc, s10, v23
	v_lshlrev_b32_e32 v130, 16, v81
	v_and_b32_e32 v131, 0xffff0000, v81
	v_lshlrev_b32_e32 v134, 16, v83
	v_and_b32_e32 v135, 0xffff0000, v83
	v_cndmask_b32_e32 v23, v23, v50, vcc
	v_rsq_f32_e32 v23, v23
	v_lshlrev_b32_e32 v138, 16, v85
	v_and_b32_e32 v139, 0xffff0000, v85
	v_lshlrev_b32_e32 v142, 16, v87
	v_and_b32_e32 v143, 0xffff0000, v87
	v_mul_f32_e32 v50, 0x45800000, v23
	s_nop 1
	v_cndmask_b32_e32 v50, v23, v50, vcc
	v_pk_mul_f32 v[24:25], v[50:51], v[128:129] op_sel_hi:[0,1]
	v_pk_mul_f32 v[26:27], v[50:51], v[130:131] op_sel_hi:[0,1]
	v_pk_mul_f32 v[28:29], v[50:51], v[132:133] op_sel_hi:[0,1]
	v_pk_mul_f32 v[30:31], v[50:51], v[134:135] op_sel_hi:[0,1]
	v_pk_mul_f32 v[32:33], v[50:51], v[136:137] op_sel_hi:[0,1]
	v_pk_mul_f32 v[34:35], v[50:51], v[138:139] op_sel_hi:[0,1]
	v_pk_mul_f32 v[36:37], v[50:51], v[140:141] op_sel_hi:[0,1]
	v_pk_mul_f32 v[38:39], v[50:51], v[142:143] op_sel_hi:[0,1]
	v_pk_mul_f32 v[24:25], v[0:1], v[24:25]
	v_pk_mul_f32 v[26:27], v[2:3], v[26:27]
	v_pk_mul_f32 v[28:29], v[4:5], v[28:29]
	v_pk_mul_f32 v[30:31], v[6:7], v[30:31]
	v_pk_mul_f32 v[32:33], v[8:9], v[32:33]
	v_pk_mul_f32 v[34:35], v[10:11], v[34:35]
	v_pk_mul_f32 v[36:37], v[12:13], v[36:37]
	v_pk_mul_f32 v[38:39], v[14:15], v[38:39]
	global_store_dwordx4 v[20:21], v[24:27], off offset:-3072
	global_store_dwordx4 v[20:21], v[28:31], off offset:-2048
	global_store_dwordx4 v[20:21], v[32:35], off offset:-1024
	global_store_dwordx4 v[20:21], v[36:39], off
	v_lshl_add_u64 v[20:21], v[20:21], 0, s[8:9]
	s_add_i32 s88, s88, s94
	s_cmp_lt_i32 s88, 0x8000
	s_cbranch_scc0 .Lfn_done
	global_load_dwordx2 v[80:81], v[18:19], off
	global_load_dwordx2 v[82:83], v[18:19], off offset:512
	global_load_dwordx2 v[84:85], v[18:19], off offset:1024
	global_load_dwordx2 v[86:87], v[18:19], off offset:1536
	global_load_dwordx4 v[88:91], v17, s[12:13] offset:48
	global_load_dwordx4 v[92:95], v17, s[12:13] offset:32
	global_load_dwordx4 v[96:99], v17, s[12:13] offset:16
	global_load_dwordx4 v[100:103], v17, s[12:13]
	s_add_i32 s22, s22, s94
	s_cmp_lt_i32 s22, 0x8000
	s_cselect_b32 s24, s6, 0
	s_cselect_b32 s25, s7, 0
	s_cselect_b32 s26, s4, 0
	s_cselect_b32 s27, s5, 0
	v_lshl_add_u64 v[18:19], v[18:19], 0, s[24:25]
	s_add_u32 s12, s12, s26
	s_addc_u32 s13, s13, s27
	s_waitcnt vmcnt(20)
	v_pk_add_f32 v[122:123], v[126:127], v[122:123]
	v_pk_add_f32 v[120:121], v[124:125], v[120:121]
	v_pk_add_f32 v[118:119], v[122:123], v[118:119]
	v_pk_add_f32 v[116:117], v[120:121], v[116:117]
	v_pk_add_f32 v[114:115], v[118:119], v[114:115]
	v_pk_add_f32 v[112:113], v[116:117], v[112:113]
	v_mov_b32_e32 v117, v114
	v_mov_b32_e32 v116, v113
	v_mov_b32_e32 v113, v115
	v_pk_add_f32 v[112:113], v[116:117], v[112:113]
	v_lshlrev_b32_e32 v128, 16, v104
	v_and_b32_e32 v129, 0xffff0000, v104
	v_lshlrev_b32_e32 v132, 16, v106
	v_and_b32_e32 v133, 0xffff0000, v106
	v_lshlrev_b32_e32 v136, 16, v108
	v_and_b32_e32 v137, 0xffff0000, v108
	v_lshlrev_b32_e32 v140, 16, v110
	v_and_b32_e32 v141, 0xffff0000, v110
	v_add_f32_e32 v23, v112, v113
	v_fmamk_f32 v23, v23, 0x3a800000, v22
	v_mul_f32_e32 v50, 0x4b800000, v23
	v_cmp_gt_f32_e32 vcc, s10, v23
	v_lshlrev_b32_e32 v130, 16, v105
	v_and_b32_e32 v131, 0xffff0000, v105
	v_lshlrev_b32_e32 v134, 16, v107
	v_and_b32_e32 v135, 0xffff0000, v107
	v_cndmask_b32_e32 v23, v23, v50, vcc
	v_rsq_f32_e32 v23, v23
	v_lshlrev_b32_e32 v138, 16, v109
	v_and_b32_e32 v139, 0xffff0000, v109
	v_lshlrev_b32_e32 v142, 16, v111
	v_and_b32_e32 v143, 0xffff0000, v111
	v_mul_f32_e32 v50, 0x45800000, v23
	s_nop 1
	v_cndmask_b32_e32 v50, v23, v50, vcc
	v_pk_mul_f32 v[24:25], v[50:51], v[128:129] op_sel_hi:[0,1]
	v_pk_mul_f32 v[26:27], v[50:51], v[130:131] op_sel_hi:[0,1]
	v_pk_mul_f32 v[28:29], v[50:51], v[132:133] op_sel_hi:[0,1]
	v_pk_mul_f32 v[30:31], v[50:51], v[134:135] op_sel_hi:[0,1]
	v_pk_mul_f32 v[32:33], v[50:51], v[136:137] op_sel_hi:[0,1]
	v_pk_mul_f32 v[34:35], v[50:51], v[138:139] op_sel_hi:[0,1]
	v_pk_mul_f32 v[36:37], v[50:51], v[140:141] op_sel_hi:[0,1]
	v_pk_mul_f32 v[38:39], v[50:51], v[142:143] op_sel_hi:[0,1]
	v_pk_mul_f32 v[24:25], v[0:1], v[24:25]
	v_pk_mul_f32 v[26:27], v[2:3], v[26:27]
	v_pk_mul_f32 v[28:29], v[4:5], v[28:29]
	v_pk_mul_f32 v[30:31], v[6:7], v[30:31]
	v_pk_mul_f32 v[32:33], v[8:9], v[32:33]
	v_pk_mul_f32 v[34:35], v[10:11], v[34:35]
	v_pk_mul_f32 v[36:37], v[12:13], v[36:37]
	v_pk_mul_f32 v[38:39], v[14:15], v[38:39]
	global_store_dwordx4 v[20:21], v[24:27], off offset:-3072
	global_store_dwordx4 v[20:21], v[28:31], off offset:-2048
	global_store_dwordx4 v[20:21], v[32:35], off offset:-1024
	global_store_dwordx4 v[20:21], v[36:39], off
	v_lshl_add_u64 v[20:21], v[20:21], 0, s[8:9]
	s_add_i32 s88, s88, s94
	s_cmp_lt_i32 s88, 0x8000
	s_cbranch_scc0 .Lfn_done
	global_load_dwordx2 v[104:105], v[18:19], off
	global_load_dwordx2 v[106:107], v[18:19], off offset:512
	global_load_dwordx2 v[108:109], v[18:19], off offset:1024
	global_load_dwordx2 v[110:111], v[18:19], off offset:1536
	global_load_dwordx4 v[112:115], v17, s[12:13] offset:48
	global_load_dwordx4 v[116:119], v17, s[12:13] offset:32
	global_load_dwordx4 v[120:123], v17, s[12:13] offset:16
	global_load_dwordx4 v[124:127], v17, s[12:13]
	s_add_i32 s22, s22, s94
	s_cmp_lt_i32 s22, 0x8000
	s_cselect_b32 s24, s6, 0
	s_cselect_b32 s25, s7, 0
	s_cselect_b32 s26, s4, 0
	s_cselect_b32 s27, s5, 0
	v_lshl_add_u64 v[18:19], v[18:19], 0, s[24:25]
	s_add_u32 s12, s12, s26
	s_addc_u32 s13, s13, s27
	s_waitcnt vmcnt(20)
	v_pk_add_f32 v[74:75], v[78:79], v[74:75]
	v_pk_add_f32 v[72:73], v[76:77], v[72:73]
	v_pk_add_f32 v[70:71], v[74:75], v[70:71]
	v_pk_add_f32 v[68:69], v[72:73], v[68:69]
	v_pk_add_f32 v[66:67], v[70:71], v[66:67]
	v_pk_add_f32 v[64:65], v[68:69], v[64:65]
	v_mov_b32_e32 v69, v66
	v_mov_b32_e32 v68, v65
	v_mov_b32_e32 v65, v67
	v_pk_add_f32 v[64:65], v[68:69], v[64:65]
	v_lshlrev_b32_e32 v128, 16, v56
	v_and_b32_e32 v129, 0xffff0000, v56
	v_lshlrev_b32_e32 v132, 16, v58
	v_and_b32_e32 v133, 0xffff0000, v58
	v_lshlrev_b32_e32 v136, 16, v60
	v_and_b32_e32 v137, 0xffff0000, v60
	v_lshlrev_b32_e32 v140, 16, v62
	v_and_b32_e32 v141, 0xffff0000, v62
	v_add_f32_e32 v23, v64, v65
	v_fmamk_f32 v23, v23, 0x3a800000, v22
	v_mul_f32_e32 v50, 0x4b800000, v23
	v_cmp_gt_f32_e32 vcc, s10, v23
	v_lshlrev_b32_e32 v130, 16, v57
	v_and_b32_e32 v131, 0xffff0000, v57
	v_lshlrev_b32_e32 v134, 16, v59
	v_and_b32_e32 v135, 0xffff0000, v59
	v_cndmask_b32_e32 v23, v23, v50, vcc
	v_rsq_f32_e32 v23, v23
	v_lshlrev_b32_e32 v138, 16, v61
	v_and_b32_e32 v139, 0xffff0000, v61
	v_lshlrev_b32_e32 v142, 16, v63
	v_and_b32_e32 v143, 0xffff0000, v63
	v_mul_f32_e32 v50, 0x45800000, v23
	s_nop 1
	v_cndmask_b32_e32 v50, v23, v50, vcc
	v_pk_mul_f32 v[24:25], v[50:51], v[128:129] op_sel_hi:[0,1]
	v_pk_mul_f32 v[26:27], v[50:51], v[130:131] op_sel_hi:[0,1]
	v_pk_mul_f32 v[28:29], v[50:51], v[132:133] op_sel_hi:[0,1]
	v_pk_mul_f32 v[30:31], v[50:51], v[134:135] op_sel_hi:[0,1]
	v_pk_mul_f32 v[32:33], v[50:51], v[136:137] op_sel_hi:[0,1]
	v_pk_mul_f32 v[34:35], v[50:51], v[138:139] op_sel_hi:[0,1]
	v_pk_mul_f32 v[36:37], v[50:51], v[140:141] op_sel_hi:[0,1]
	v_pk_mul_f32 v[38:39], v[50:51], v[142:143] op_sel_hi:[0,1]
	v_pk_mul_f32 v[24:25], v[0:1], v[24:25]
	v_pk_mul_f32 v[26:27], v[2:3], v[26:27]
	v_pk_mul_f32 v[28:29], v[4:5], v[28:29]
	v_pk_mul_f32 v[30:31], v[6:7], v[30:31]
	v_pk_mul_f32 v[32:33], v[8:9], v[32:33]
	v_pk_mul_f32 v[34:35], v[10:11], v[34:35]
	v_pk_mul_f32 v[36:37], v[12:13], v[36:37]
	v_pk_mul_f32 v[38:39], v[14:15], v[38:39]
	global_store_dwordx4 v[20:21], v[24:27], off offset:-3072
	global_store_dwordx4 v[20:21], v[28:31], off offset:-2048
	global_store_dwordx4 v[20:21], v[32:35], off offset:-1024
	global_store_dwordx4 v[20:21], v[36:39], off
	v_lshl_add_u64 v[20:21], v[20:21], 0, s[8:9]
	s_add_i32 s88, s88, s94
	s_cmp_lt_i32 s88, 0x8000
	s_cbranch_scc1 .Lfn_loop
.Lfn_done:
.LBB0_2815:
	s_cmp_lt_i32 s87, 19
	s_cselect_b64 s[0:1], -1, 0
	s_xor_b64 s[2:3], s[2:3], -1
	s_or_b64 s[0:1], s[2:3], s[0:1]
	s_and_b64 vcc, exec, s[0:1]
	s_cbranch_vccnz .LBB0_2869
	s_waitcnt vmcnt(0)
	s_waitcnt vmcnt(0)
	s_barrier
	s_mov_b64 s[0:1], exec
	v_readlane_b32 s2, v251, 1
	v_readlane_b32 s3, v251, 2
	s_and_b64 s[2:3], s[0:1], s[2:3]
	s_mov_b64 exec, s[2:3]
	s_cbranch_execz .LBB0_2868
	s_add_i32 s2, 0, 0x23fc0
	v_mov_b32_e32 v0, s2
	s_waitcnt vmcnt(0) expcnt(0) lgkmcnt(0)
	ds_read_b32 v2, v0
	s_add_i32 s2, 0, 0x23fc4
	v_mov_b32_e32 v0, s2
	ds_read_b32 v0, v0
	s_waitcnt lgkmcnt(1)
	v_cmp_ne_u32_e32 vcc, 0, v2
	s_cbranch_vccnz .LBB0_2832
	v_readlane_b32 s2, v251, 0
	s_mul_i32 s16, s93, s2
	s_add_u32 s2, s96, 0x1000
	s_addc_u32 s3, s97, 0
	s_add_u32 s4, s96, 0x1100
	s_addc_u32 s5, s97, 0
	s_add_u32 s6, s96, 0x1200
	s_addc_u32 s7, s97, 0
	s_add_u32 s8, s96, 0x1300
	s_mul_i32 s16, s16, s92
	s_addc_u32 s9, s97, 0
	s_mov_b32 s17, 1
	v_mov_b32_e32 v16, 0
	s_branch .LBB0_2820
